# GEMM K-loops: loading wave runs its load segment at s_setprio 2 (above the computing partner's 1)
# baseline (speedup 1.0000x reference)
; #define PG8_STAGE(bufoff, gbase, voff) do { _Pragma("unroll") for (int _i = 0; _i < 2; ++_i) \
;         __builtin_amdgcn_global_load_lds((const unsigned*)((const char*)(gbase) + (voff)[_i]), (PG8_LAS unsigned*)(lds + (bufoff) + ldsw + _i * 8192), 16, 0, 0); } while (0)
; #define PG8_LDA(dst, b, h) do { _Pragma("unroll") for (int m = 0; m < 4; ++m) _Pragma("unroll") for (int k = 0; k < 2; ++k) dst[m][k] = *(const PG8_LAS bf16x8*)(lds + PG8_SA(b, h) + aoff + m * 2048 + k * 1024); } while (0)
; #define PG8_LDB(dst, b, h) do { _Pragma("unroll") for (int n = 0; n < 2; ++n) _Pragma("unroll") for (int k = 0; k < 2; ++k) dst[n][k] = *(const PG8_LAS bf16x8*)(lds + PG8_SB(b, h) + boff + n * 2048 + k * 1024); } while (0)
; #define PG8_MMA(ai, bj, At, Bt) do { __builtin_amdgcn_s_setprio(1); _Pragma("unroll") for (int m = 0; m < 4; ++m) _Pragma("unroll") for (int n = 0; n < 2; ++n) _Pragma("unroll") for (int k = 0; k < 2; ++k) \
;         acc[ai][bj][m][n] = __builtin_amdgcn_mfma_f32_16x16x32_bf16(Bt[n][k], At[m][k], acc[ai][bj][m][n], 0, 0, 0); __builtin_amdgcn_s_setprio(0); } while (0)
; #define PG8_WAIT_V(n) asm volatile("s_waitcnt vmcnt(" #n ")" ::: "memory")
; #define PG8_WAIT_L(n) asm volatile("s_waitcnt lgkmcnt(" #n ")" ::: "memory")
; #define PG8_BAR __builtin_amdgcn_s_barrier()
; template <class Epi, class Sched, bool ALIGN_EPI = false, bool SP2 = false>
; __device__ __forceinline__ void gemm_phase(PG8_LAS unsigned char* lds, const Gemm g, const Sched& S, const Epi& E) {
;     ...
;             const char* a1 = cA + (size_t)(t + 1) * kstep;
;             const char* a2 = last ? nA : cA + (size_t)(t + 2) * kstep; const char* b2 = last ? nB : cB + (size_t)(t + 2) * kstep;
;             const char* a3 = a2 + kstep; const char* b3 = b2 + kstep;
;             if (last && has_next) S.a_ready(nxt);
;             if constexpr (SP2) {
;             PG8_LDB(B0, 0, 0); PG8_LDB(B1, 0, 1); PG8_SCHED; PG8_LDA(At, 0, 0); PG8_STAGE(PG8_SA(1, 1), a1 + hstep, voffA);
;             PG8_WAIT_V(8); PG8_WAIT_L(0); PG8_BAR; PG8_MMA(0, 0, At, B0); PG8_MMA(0, 1, At, B1); PG8_BAR; PG8_SCHED;
;             PG8_LDA(At, 0, 1); PG8_STAGE(PG8_SB(0, 0), b2, voffB); PG8_STAGE(PG8_SB(0, 1), b2 + hstep, voffB); PG8_STAGE(PG8_SA(0, 0), a2, voffA);
;             PG8_WAIT_V(8); PG8_WAIT_L(0); PG8_BAR; PG8_MMA(1, 0, At, B0); PG8_MMA(1, 1, At, B1); PG8_BAR; PG8_SCHED;
.LBB0_104:
	s_setprio 2
	ds_read_b128 v[128:131], v173
	ds_read_b128 v[132:135], v173 offset:1024
	ds_read_b128 v[156:159], v173 offset:2048
	ds_read_b128 v[180:183], v173 offset:3072
	ds_read_b128 v[184:187], v174
	ds_read_b128 v[188:191], v174 offset:1024
	ds_read_b128 v[192:195], v174 offset:2048
	ds_read_b128 v[200:203], v174 offset:3072
	s_add_u32 s2, s30, 0xfff80080
	s_addc_u32 s3, s31, -1
	s_cmp_eq_u32 s73, 28
	s_cselect_b32 s5, s7, s3
	s_cselect_b32 s4, s23, s2
	s_cselect_b32 s3, s21, s72
	s_cselect_b32 s2, s70, s71
	s_add_i32 m0, s29, 0xc000
	ds_read_b128 v[204:207], v175
	ds_read_b128 v[208:211], v175 offset:1024
	ds_read_b128 v[212:215], v175 offset:2048
	ds_read_b128 v[216:219], v175 offset:3072
	ds_read_b128 v[220:223], v175 offset:4096
	ds_read_b128 v[224:227], v175 offset:5120
	ds_read_b128 v[228:231], v175 offset:6144
	ds_read_b128 v[232:235], v175 offset:7168
	global_load_lds_dwordx4 v146, s[30:31]
	s_add_i32 m0, s29, 0xe000
	s_nop 0
	global_load_lds_dwordx4 v148, s[30:31]
	s_waitcnt vmcnt(8)
	s_waitcnt lgkmcnt(0)
	s_barrier
	s_setprio 1
	s_waitcnt lgkmcnt(0)
	v_mfma_f32_16x16x32_bf16 v[124:127], v[128:131], v[204:207], v[124:127]
	v_mfma_f32_16x16x32_bf16 v[120:123], v[156:159], v[204:207], v[120:123]
	v_mfma_f32_16x16x32_bf16 v[116:119], v[128:131], v[212:215], v[116:119]
	v_mfma_f32_16x16x32_bf16 v[112:115], v[156:159], v[212:215], v[112:115]
	v_mfma_f32_16x16x32_bf16 v[100:103], v[128:131], v[220:223], v[100:103]
	v_mfma_f32_16x16x32_bf16 v[96:99], v[156:159], v[220:223], v[96:99]
	v_mfma_f32_16x16x32_bf16 v[84:87], v[128:131], v[228:231], v[84:87]
	v_mfma_f32_16x16x32_bf16 v[80:83], v[156:159], v[228:231], v[80:83]
	v_mfma_f32_16x16x32_bf16 v[124:127], v[132:135], v[208:211], v[124:127]
	v_mfma_f32_16x16x32_bf16 v[120:123], v[180:183], v[208:211], v[120:123]
	v_mfma_f32_16x16x32_bf16 v[116:119], v[132:135], v[216:219], v[116:119]
	v_mfma_f32_16x16x32_bf16 v[112:115], v[180:183], v[216:219], v[112:115]
	v_mfma_f32_16x16x32_bf16 v[100:103], v[132:135], v[224:227], v[100:103]
	v_mfma_f32_16x16x32_bf16 v[96:99], v[180:183], v[224:227], v[96:99]
	v_mfma_f32_16x16x32_bf16 v[84:87], v[132:135], v[232:235], v[84:87]
	v_mfma_f32_16x16x32_bf16 v[80:83], v[180:183], v[232:235], v[80:83]
	s_setprio 0
	s_setprio 1
	v_mfma_f32_16x16x32_bf16 v[108:111], v[184:187], v[204:207], v[108:111]
	v_mfma_f32_16x16x32_bf16 v[104:107], v[192:195], v[204:207], v[104:107]
	v_mfma_f32_16x16x32_bf16 v[92:95], v[184:187], v[212:215], v[92:95]
	v_mfma_f32_16x16x32_bf16 v[88:91], v[192:195], v[212:215], v[88:91]
	v_mfma_f32_16x16x32_bf16 v[76:79], v[184:187], v[220:223], v[76:79]
	v_mfma_f32_16x16x32_bf16 v[72:75], v[192:195], v[220:223], v[72:75]
	v_mfma_f32_16x16x32_bf16 v[68:71], v[184:187], v[228:231], v[68:71]
	v_mfma_f32_16x16x32_bf16 v[64:67], v[192:195], v[228:231], v[64:67]
	v_mfma_f32_16x16x32_bf16 v[108:111], v[188:191], v[208:211], v[108:111]
	v_mfma_f32_16x16x32_bf16 v[104:107], v[200:203], v[208:211], v[104:107]
	v_mfma_f32_16x16x32_bf16 v[92:95], v[188:191], v[216:219], v[92:95]
	v_mfma_f32_16x16x32_bf16 v[88:91], v[200:203], v[216:219], v[88:91]
	v_mfma_f32_16x16x32_bf16 v[76:79], v[188:191], v[224:227], v[76:79]
	v_mfma_f32_16x16x32_bf16 v[72:75], v[200:203], v[224:227], v[72:75]
	v_mfma_f32_16x16x32_bf16 v[68:71], v[188:191], v[232:235], v[68:71]
	v_mfma_f32_16x16x32_bf16 v[64:67], v[200:203], v[232:235], v[64:67]
	s_setprio 0
	s_barrier
	s_setprio 2
	s_add_u32 s98, s2, s14
	s_addc_u32 s99, s3, s15
	s_add_u32 s100, s4, s14
	s_addc_u32 s101, s5, s15
	s_add_i32 s74, s57, s33
	s_mov_b32 m0, s74
	ds_read_b128 v[204:207], v175 offset:16384
	ds_read_b128 v[208:211], v175 offset:17408
	ds_read_b128 v[212:215], v175 offset:18432
	ds_read_b128 v[216:219], v175 offset:19456
	ds_read_b128 v[220:223], v175 offset:20480
	ds_read_b128 v[224:227], v175 offset:21504
	ds_read_b128 v[228:231], v175 offset:22528
	ds_read_b128 v[232:235], v175 offset:23552
	global_load_lds_dwordx4 v138, s[2:3]
	s_add_i32 m0, s74, 0x2000
	s_add_u32 s74, s2, 0x80000
	s_addc_u32 s75, s3, 0
	s_add_i32 s76, s68, s33
	global_load_lds_dwordx4 v142, s[2:3]
	s_mov_b32 m0, s76
	s_nop 0
	global_load_lds_dwordx4 v138, s[74:75]
	s_add_i32 m0, s76, 0x2000
	s_nop 0
	global_load_lds_dwordx4 v142, s[74:75]
	s_mov_b32 m0, s29
	s_nop 0
	global_load_lds_dwordx4 v136, s[4:5]
	s_mov_b32 m0, s34
	s_nop 0
	global_load_lds_dwordx4 v140, s[4:5]
	s_waitcnt vmcnt(8)
	s_waitcnt lgkmcnt(0)
	s_barrier
	s_setprio 1
	s_waitcnt lgkmcnt(0)
	v_mfma_f32_16x16x32_bf16 v[60:63], v[128:131], v[204:207], v[60:63]
	v_mfma_f32_16x16x32_bf16 v[56:59], v[156:159], v[204:207], v[56:59]
	v_mfma_f32_16x16x32_bf16 v[52:55], v[128:131], v[212:215], v[52:55]
	v_mfma_f32_16x16x32_bf16 v[48:51], v[156:159], v[212:215], v[48:51]
	v_mfma_f32_16x16x32_bf16 v[36:39], v[128:131], v[220:223], v[36:39]
	v_mfma_f32_16x16x32_bf16 v[32:35], v[156:159], v[220:223], v[32:35]
	v_mfma_f32_16x16x32_bf16 v[20:23], v[128:131], v[228:231], v[20:23]
	v_mfma_f32_16x16x32_bf16 v[16:19], v[156:159], v[228:231], v[16:19]
	v_mfma_f32_16x16x32_bf16 v[60:63], v[132:135], v[208:211], v[60:63]
	v_mfma_f32_16x16x32_bf16 v[56:59], v[180:183], v[208:211], v[56:59]
	v_mfma_f32_16x16x32_bf16 v[52:55], v[132:135], v[216:219], v[52:55]
	v_mfma_f32_16x16x32_bf16 v[48:51], v[180:183], v[216:219], v[48:51]
	v_mfma_f32_16x16x32_bf16 v[36:39], v[132:135], v[224:227], v[36:39]
	v_mfma_f32_16x16x32_bf16 v[32:35], v[180:183], v[224:227], v[32:35]
	v_mfma_f32_16x16x32_bf16 v[20:23], v[132:135], v[232:235], v[20:23]
	v_mfma_f32_16x16x32_bf16 v[16:19], v[180:183], v[232:235], v[16:19]
	s_setprio 0
	s_setprio 1
	v_mfma_f32_16x16x32_bf16 v[44:47], v[184:187], v[204:207], v[44:47]
	v_mfma_f32_16x16x32_bf16 v[40:43], v[192:195], v[204:207], v[40:43]
	v_mfma_f32_16x16x32_bf16 v[28:31], v[184:187], v[212:215], v[28:31]
	v_mfma_f32_16x16x32_bf16 v[24:27], v[192:195], v[212:215], v[24:27]
	v_mfma_f32_16x16x32_bf16 v[12:15], v[184:187], v[220:223], v[12:15]
	v_mfma_f32_16x16x32_bf16 v[8:11], v[192:195], v[220:223], v[8:11]
	v_mfma_f32_16x16x32_bf16 v[4:7], v[184:187], v[228:231], v[4:7]
	v_mfma_f32_16x16x32_bf16 v[0:3], v[192:195], v[228:231], v[0:3]
	v_mfma_f32_16x16x32_bf16 v[44:47], v[188:191], v[208:211], v[44:47]
	v_mfma_f32_16x16x32_bf16 v[40:43], v[200:203], v[208:211], v[40:43]
	v_mfma_f32_16x16x32_bf16 v[28:31], v[188:191], v[216:219], v[28:31]
	v_mfma_f32_16x16x32_bf16 v[24:27], v[200:203], v[216:219], v[24:27]
	v_mfma_f32_16x16x32_bf16 v[12:15], v[188:191], v[224:227], v[12:15]
	v_mfma_f32_16x16x32_bf16 v[8:11], v[200:203], v[224:227], v[8:11]
	v_mfma_f32_16x16x32_bf16 v[4:7], v[188:191], v[232:235], v[4:7]
	v_mfma_f32_16x16x32_bf16 v[0:3], v[200:203], v[232:235], v[0:3]
	s_setprio 0
	s_barrier
; #define PG8_STAGE(bufoff, gbase, voff) do { _Pragma("unroll") for (int _i = 0; _i < 2; ++_i) \
;         __builtin_amdgcn_global_load_lds((const unsigned*)((const char*)(gbase) + (voff)[_i]), (PG8_LAS unsigned*)(lds + (bufoff) + ldsw + _i * 8192), 16, 0, 0); } while (0)
; #define PG8_LDA(dst, b, h) do { _Pragma("unroll") for (int m = 0; m < 4; ++m) _Pragma("unroll") for (int k = 0; k < 2; ++k) dst[m][k] = *(const PG8_LAS bf16x8*)(lds + PG8_SA(b, h) + aoff + m * 2048 + k * 1024); } while (0)
; #define PG8_LDB(dst, b, h) do { _Pragma("unroll") for (int n = 0; n < 2; ++n) _Pragma("unroll") for (int k = 0; k < 2; ++k) dst[n][k] = *(const PG8_LAS bf16x8*)(lds + PG8_SB(b, h) + boff + n * 2048 + k * 1024); } while (0)
; #define PG8_MMA(ai, bj, At, Bt) do { __builtin_amdgcn_s_setprio(1); _Pragma("unroll") for (int m = 0; m < 4; ++m) _Pragma("unroll") for (int n = 0; n < 2; ++n) _Pragma("unroll") for (int k = 0; k < 2; ++k) \
;         acc[ai][bj][m][n] = __builtin_amdgcn_mfma_f32_16x16x32_bf16(Bt[n][k], At[m][k], acc[ai][bj][m][n], 0, 0, 0); __builtin_amdgcn_s_setprio(0); } while (0)
; #define PG8_WAIT_V(n) asm volatile("s_waitcnt vmcnt(" #n ")" ::: "memory")
; #define PG8_WAIT_L(n) asm volatile("s_waitcnt lgkmcnt(" #n ")" ::: "memory")
; #define PG8_BAR __builtin_amdgcn_s_barrier()
; #define PG8_SCHED __builtin_amdgcn_sched_barrier(0)
; template <class Epi, class Sched, bool ALIGN_EPI = false, bool SP2 = false>
; __device__ __forceinline__ void gemm_phase(PG8_LAS unsigned char* lds, const Gemm g, const Sched& S, const Epi& E) {
;     ...
;             PG8_LDB(B0, 1, 0); PG8_LDB(B1, 1, 1); PG8_SCHED; PG8_LDA(At, 1, 0); PG8_STAGE(PG8_SA(0, 1), a2 + hstep, voffA);
;             PG8_WAIT_V(8); PG8_WAIT_L(0); PG8_BAR; PG8_MMA(0, 0, At, B0); PG8_MMA(0, 1, At, B1); PG8_BAR; PG8_SCHED;
;             PG8_LDA(At, 1, 1); PG8_STAGE(PG8_SB(1, 0), b3, voffB); PG8_STAGE(PG8_SB(1, 1), b3 + hstep, voffB); PG8_STAGE(PG8_SA(1, 0), a3, voffA);
;             PG8_WAIT_V(8); PG8_WAIT_L(0); PG8_BAR; PG8_MMA(1, 0, At, B0); PG8_MMA(1, 1, At, B1); PG8_BAR; PG8_SCHED;
;     ...
;         if constexpr (ALIGN_EPI) { if (wr == 0) PG8_BAR; }
;         if constexpr (!Epi::AFTER_DRAIN) { E(acc, cur, wr, wc, fr, fq); S.done(cur); }
;         if (!has_next) break;
	s_setprio 2
	s_add_i32 s74, 0, 0x18000
	v_add_u32_e32 v144, s74, v161
	s_add_i32 s75, 0, 0x1c000
	ds_read_b128 v[128:131], v144
	ds_read_b128 v[132:135], v144 offset:1024
	ds_read_b128 v[156:159], v144 offset:2048
	ds_read_b128 v[180:183], v144 offset:3072
	v_add_u32_e32 v144, s75, v161
	ds_read_b128 v[184:187], v144
	ds_read_b128 v[188:191], v144 offset:1024
	ds_read_b128 v[192:195], v144 offset:2048
	ds_read_b128 v[200:203], v144 offset:3072
	s_add_u32 s4, s4, 0x80000
	s_addc_u32 s5, s5, 0
	s_mov_b32 m0, s35
	ds_read_b128 v[204:207], v175 offset:32768
	ds_read_b128 v[208:211], v175 offset:33792
	ds_read_b128 v[212:215], v175 offset:34816
	ds_read_b128 v[216:219], v175 offset:35840
	ds_read_b128 v[220:223], v175 offset:36864
	ds_read_b128 v[224:227], v175 offset:37888
	ds_read_b128 v[228:231], v175 offset:38912
	ds_read_b128 v[232:235], v175 offset:39936
	global_load_lds_dwordx4 v136, s[4:5]
	s_mov_b32 m0, s36
	s_nop 0
	global_load_lds_dwordx4 v140, s[4:5]
	s_waitcnt vmcnt(8)
	s_waitcnt lgkmcnt(0)
	s_barrier
	s_setprio 1
	s_waitcnt lgkmcnt(0)
	v_mfma_f32_16x16x32_bf16 v[124:127], v[128:131], v[204:207], v[124:127]
	v_mfma_f32_16x16x32_bf16 v[120:123], v[156:159], v[204:207], v[120:123]
	v_mfma_f32_16x16x32_bf16 v[116:119], v[128:131], v[212:215], v[116:119]
	v_mfma_f32_16x16x32_bf16 v[112:115], v[156:159], v[212:215], v[112:115]
	v_mfma_f32_16x16x32_bf16 v[100:103], v[128:131], v[220:223], v[100:103]
	v_mfma_f32_16x16x32_bf16 v[96:99], v[156:159], v[220:223], v[96:99]
	v_mfma_f32_16x16x32_bf16 v[84:87], v[128:131], v[228:231], v[84:87]
	v_mfma_f32_16x16x32_bf16 v[80:83], v[156:159], v[228:231], v[80:83]
	v_mfma_f32_16x16x32_bf16 v[124:127], v[132:135], v[208:211], v[124:127]
	v_mfma_f32_16x16x32_bf16 v[120:123], v[180:183], v[208:211], v[120:123]
	v_mfma_f32_16x16x32_bf16 v[116:119], v[132:135], v[216:219], v[116:119]
	v_mfma_f32_16x16x32_bf16 v[112:115], v[180:183], v[216:219], v[112:115]
	v_mfma_f32_16x16x32_bf16 v[100:103], v[132:135], v[224:227], v[100:103]
	v_mfma_f32_16x16x32_bf16 v[96:99], v[180:183], v[224:227], v[96:99]
	v_mfma_f32_16x16x32_bf16 v[84:87], v[132:135], v[232:235], v[84:87]
	v_mfma_f32_16x16x32_bf16 v[80:83], v[180:183], v[232:235], v[80:83]
	s_setprio 0
	s_setprio 1
	v_mfma_f32_16x16x32_bf16 v[108:111], v[184:187], v[204:207], v[108:111]
	v_mfma_f32_16x16x32_bf16 v[104:107], v[192:195], v[204:207], v[104:107]
	v_mfma_f32_16x16x32_bf16 v[92:95], v[184:187], v[212:215], v[92:95]
	v_mfma_f32_16x16x32_bf16 v[88:91], v[192:195], v[212:215], v[88:91]
	v_mfma_f32_16x16x32_bf16 v[76:79], v[184:187], v[220:223], v[76:79]
	v_mfma_f32_16x16x32_bf16 v[72:75], v[192:195], v[220:223], v[72:75]
	v_mfma_f32_16x16x32_bf16 v[68:71], v[184:187], v[228:231], v[68:71]
	v_mfma_f32_16x16x32_bf16 v[64:67], v[192:195], v[228:231], v[64:67]
	v_mfma_f32_16x16x32_bf16 v[108:111], v[188:191], v[208:211], v[108:111]
	v_mfma_f32_16x16x32_bf16 v[104:107], v[200:203], v[208:211], v[104:107]
	v_mfma_f32_16x16x32_bf16 v[92:95], v[188:191], v[216:219], v[92:95]
	v_mfma_f32_16x16x32_bf16 v[88:91], v[200:203], v[216:219], v[88:91]
	v_mfma_f32_16x16x32_bf16 v[76:79], v[188:191], v[224:227], v[76:79]
	v_mfma_f32_16x16x32_bf16 v[72:75], v[200:203], v[224:227], v[72:75]
	v_mfma_f32_16x16x32_bf16 v[68:71], v[188:191], v[232:235], v[68:71]
	v_mfma_f32_16x16x32_bf16 v[64:67], v[200:203], v[232:235], v[64:67]
	s_setprio 0
	s_barrier
	s_setprio 2
	s_add_i32 s4, s74, s33
	s_mov_b32 m0, s4
	ds_read_b128 v[204:207], v175 offset:49152
	ds_read_b128 v[208:211], v175 offset:50176
	ds_read_b128 v[212:215], v175 offset:51200
	ds_read_b128 v[216:219], v175 offset:52224
	ds_read_b128 v[220:223], v175 offset:53248
	ds_read_b128 v[224:227], v175 offset:54272
	ds_read_b128 v[228:231], v175 offset:55296
	ds_read_b128 v[232:235], v175 offset:56320
	global_load_lds_dwordx4 v138, s[98:99]
	s_add_i32 m0, s4, 0x2000
	s_add_u32 s2, s2, 0x80080
	s_addc_u32 s3, s3, 0
	s_add_i32 s4, s75, s33
	global_load_lds_dwordx4 v142, s[98:99]
	s_mov_b32 m0, s4
	s_nop 0
	global_load_lds_dwordx4 v138, s[2:3]
	s_add_i32 m0, s4, 0x2000
	s_nop 0
	global_load_lds_dwordx4 v142, s[2:3]
	s_mov_b32 m0, s41
	s_nop 0
	global_load_lds_dwordx4 v136, s[100:101]
	s_mov_b32 m0, s42
	s_nop 0
	global_load_lds_dwordx4 v140, s[100:101]
	s_waitcnt vmcnt(8)
	s_waitcnt lgkmcnt(0)
	s_barrier
	s_setprio 1
	s_waitcnt lgkmcnt(0)
	v_mfma_f32_16x16x32_bf16 v[60:63], v[128:131], v[204:207], v[60:63]
	v_mfma_f32_16x16x32_bf16 v[56:59], v[156:159], v[204:207], v[56:59]
	v_mfma_f32_16x16x32_bf16 v[52:55], v[128:131], v[212:215], v[52:55]
	v_mfma_f32_16x16x32_bf16 v[48:51], v[156:159], v[212:215], v[48:51]
	v_mfma_f32_16x16x32_bf16 v[36:39], v[128:131], v[220:223], v[36:39]
	v_mfma_f32_16x16x32_bf16 v[32:35], v[156:159], v[220:223], v[32:35]
	v_mfma_f32_16x16x32_bf16 v[20:23], v[128:131], v[228:231], v[20:23]
	v_mfma_f32_16x16x32_bf16 v[16:19], v[156:159], v[228:231], v[16:19]
	v_mfma_f32_16x16x32_bf16 v[60:63], v[132:135], v[208:211], v[60:63]
	v_mfma_f32_16x16x32_bf16 v[56:59], v[180:183], v[208:211], v[56:59]
	v_mfma_f32_16x16x32_bf16 v[52:55], v[132:135], v[216:219], v[52:55]
	v_mfma_f32_16x16x32_bf16 v[48:51], v[180:183], v[216:219], v[48:51]
	v_mfma_f32_16x16x32_bf16 v[36:39], v[132:135], v[224:227], v[36:39]
	v_mfma_f32_16x16x32_bf16 v[32:35], v[180:183], v[224:227], v[32:35]
	v_mfma_f32_16x16x32_bf16 v[20:23], v[132:135], v[232:235], v[20:23]
	v_mfma_f32_16x16x32_bf16 v[16:19], v[180:183], v[232:235], v[16:19]
	s_setprio 0
	s_setprio 1
	v_mfma_f32_16x16x32_bf16 v[44:47], v[184:187], v[204:207], v[44:47]
	v_mfma_f32_16x16x32_bf16 v[40:43], v[192:195], v[204:207], v[40:43]
	v_mfma_f32_16x16x32_bf16 v[28:31], v[184:187], v[212:215], v[28:31]
	v_mfma_f32_16x16x32_bf16 v[24:27], v[192:195], v[212:215], v[24:27]
	v_mfma_f32_16x16x32_bf16 v[12:15], v[184:187], v[220:223], v[12:15]
	v_mfma_f32_16x16x32_bf16 v[8:11], v[192:195], v[220:223], v[8:11]
	v_mfma_f32_16x16x32_bf16 v[4:7], v[184:187], v[228:231], v[4:7]
	v_mfma_f32_16x16x32_bf16 v[0:3], v[192:195], v[228:231], v[0:3]
	v_mfma_f32_16x16x32_bf16 v[44:47], v[188:191], v[208:211], v[44:47]
	v_mfma_f32_16x16x32_bf16 v[40:43], v[200:203], v[208:211], v[40:43]
	v_mfma_f32_16x16x32_bf16 v[28:31], v[188:191], v[216:219], v[28:31]
	v_mfma_f32_16x16x32_bf16 v[24:27], v[200:203], v[216:219], v[24:27]
	v_mfma_f32_16x16x32_bf16 v[12:15], v[188:191], v[224:227], v[12:15]
	v_mfma_f32_16x16x32_bf16 v[8:11], v[200:203], v[224:227], v[8:11]
	v_mfma_f32_16x16x32_bf16 v[4:7], v[188:191], v[232:235], v[4:7]
	v_mfma_f32_16x16x32_bf16 v[0:3], v[200:203], v[232:235], v[0:3]
	s_setprio 0
	s_barrier
	s_add_i32 s73, s73, 2
	s_add_u32 s30, s30, 0x100
	s_addc_u32 s31, s31, 0
	s_add_u32 s71, s71, 0x100
	s_addc_u32 s72, s72, 0
	s_cmp_gt_u32 s73, 29
	s_cbranch_scc0 .LBB0_104
	s_and_b64 vcc, exec, s[16:17]
	s_cbranch_vccz .LBB0_107
	s_barrier

; #define PG8_STAGE(bufoff, gbase, voff) do { _Pragma("unroll") for (int _i = 0; _i < 2; ++_i) \
;         __builtin_amdgcn_global_load_lds((const unsigned*)((const char*)(gbase) + (voff)[_i]), (PG8_LAS unsigned*)(lds + (bufoff) + ldsw + _i * 8192), 16, 0, 0); } while (0)
; #define PG8_LDA(dst, b, h) do { _Pragma("unroll") for (int m = 0; m < 4; ++m) _Pragma("unroll") for (int k = 0; k < 2; ++k) dst[m][k] = *(const PG8_LAS bf16x8*)(lds + PG8_SA(b, h) + aoff + m * 2048 + k * 1024); } while (0)
; #define PG8_LDB(dst, b, h) do { _Pragma("unroll") for (int n = 0; n < 2; ++n) _Pragma("unroll") for (int k = 0; k < 2; ++k) dst[n][k] = *(const PG8_LAS bf16x8*)(lds + PG8_SB(b, h) + boff + n * 2048 + k * 1024); } while (0)
; #define PG8_MMA(ai, bj, At, Bt) do { __builtin_amdgcn_s_setprio(1); _Pragma("unroll") for (int m = 0; m < 4; ++m) _Pragma("unroll") for (int n = 0; n < 2; ++n) _Pragma("unroll") for (int k = 0; k < 2; ++k) \
;         acc[ai][bj][m][n] = __builtin_amdgcn_mfma_f32_16x16x32_bf16(Bt[n][k], At[m][k], acc[ai][bj][m][n], 0, 0, 0); __builtin_amdgcn_s_setprio(0); } while (0)
; #define PG8_WAIT_V(n) asm volatile("s_waitcnt vmcnt(" #n ")" ::: "memory")
; #define PG8_WAIT_L(n) asm volatile("s_waitcnt lgkmcnt(" #n ")" ::: "memory")
; #define PG8_BAR __builtin_amdgcn_s_barrier()
; template <class Epi, class Sched, bool ALIGN_EPI = false, bool SP2 = false>
; __device__ __forceinline__ void gemm_phase(PG8_LAS unsigned char* lds, const Gemm g, const Sched& S, const Epi& E) {
;     ...
;             const char* a1 = cA + (size_t)(t + 1) * kstep;
;             const char* a2 = last ? nA : cA + (size_t)(t + 2) * kstep; const char* b2 = last ? nB : cB + (size_t)(t + 2) * kstep;
;             const char* a3 = a2 + kstep; const char* b3 = b2 + kstep;
;             if (last && has_next) S.a_ready(nxt);
;             if constexpr (SP2) {
;             PG8_LDB(B0, 0, 0); PG8_LDB(B1, 0, 1); PG8_SCHED; PG8_LDA(At, 0, 0); PG8_STAGE(PG8_SA(1, 1), a1 + hstep, voffA);
;             PG8_WAIT_V(8); PG8_WAIT_L(0); PG8_BAR; PG8_MMA(0, 0, At, B0); PG8_MMA(0, 1, At, B1); PG8_BAR; PG8_SCHED;
;             PG8_LDA(At, 0, 1); PG8_STAGE(PG8_SB(0, 0), b2, voffB); PG8_STAGE(PG8_SB(0, 1), b2 + hstep, voffB); PG8_STAGE(PG8_SA(0, 0), a2, voffA);
;             PG8_WAIT_V(8); PG8_WAIT_L(0); PG8_BAR; PG8_MMA(1, 0, At, B0); PG8_MMA(1, 1, At, B1); PG8_BAR; PG8_SCHED;
.LBB0_527:
	s_setprio 2
	ds_read_b128 v[144:147], v158
	ds_read_b128 v[162:165], v158 offset:1024
	ds_read_b128 v[166:169], v158 offset:2048
	ds_read_b128 v[170:173], v158 offset:3072
	ds_read_b128 v[174:177], v159
	ds_read_b128 v[178:181], v159 offset:1024
	ds_read_b128 v[182:185], v159 offset:2048
	ds_read_b128 v[186:189], v159 offset:3072
	s_add_u32 s2, s28, 0xfff80080
	s_addc_u32 s3, s29, -1
	s_cmp_eq_u32 s58, 28
	s_cselect_b32 s31, s21, s3
	s_cselect_b32 s30, s27, s2
	s_cselect_b32 s3, s19, s53
	s_cselect_b32 s2, s51, s52
	s_add_i32 m0, s34, 0xc000
	ds_read_b128 v[190:193], v160
	ds_read_b128 v[194:197], v160 offset:1024
	ds_read_b128 v[200:203], v160 offset:2048
	ds_read_b128 v[204:207], v160 offset:3072
	ds_read_b128 v[208:211], v160 offset:4096
	ds_read_b128 v[212:215], v160 offset:5120
	ds_read_b128 v[216:219], v160 offset:6144
	ds_read_b128 v[220:223], v160 offset:7168
	global_load_lds_dwordx4 v136, s[28:29]
	s_add_i32 m0, s34, 0xe000
	s_nop 0
	global_load_lds_dwordx4 v138, s[28:29]
	s_waitcnt vmcnt(8)
	s_waitcnt lgkmcnt(0)
	s_barrier
	s_setprio 1
	s_waitcnt lgkmcnt(0)
	v_mfma_f32_16x16x32_bf16 v[124:127], v[144:147], v[190:193], v[124:127]
	v_mfma_f32_16x16x32_bf16 v[120:123], v[166:169], v[190:193], v[120:123]
	v_mfma_f32_16x16x32_bf16 v[108:111], v[144:147], v[200:203], v[108:111]
	v_mfma_f32_16x16x32_bf16 v[104:107], v[166:169], v[200:203], v[104:107]
	v_mfma_f32_16x16x32_bf16 v[92:95], v[144:147], v[208:211], v[92:95]
	v_mfma_f32_16x16x32_bf16 v[88:91], v[166:169], v[208:211], v[88:91]
	v_mfma_f32_16x16x32_bf16 v[76:79], v[144:147], v[216:219], v[76:79]
	v_mfma_f32_16x16x32_bf16 v[72:75], v[166:169], v[216:219], v[72:75]
	v_mfma_f32_16x16x32_bf16 v[124:127], v[162:165], v[194:197], v[124:127]
	v_mfma_f32_16x16x32_bf16 v[120:123], v[170:173], v[194:197], v[120:123]
	v_mfma_f32_16x16x32_bf16 v[108:111], v[162:165], v[204:207], v[108:111]
	v_mfma_f32_16x16x32_bf16 v[104:107], v[170:173], v[204:207], v[104:107]
	v_mfma_f32_16x16x32_bf16 v[92:95], v[162:165], v[212:215], v[92:95]
	v_mfma_f32_16x16x32_bf16 v[88:91], v[170:173], v[212:215], v[88:91]
	v_mfma_f32_16x16x32_bf16 v[76:79], v[162:165], v[220:223], v[76:79]
	v_mfma_f32_16x16x32_bf16 v[72:75], v[170:173], v[220:223], v[72:75]
	s_setprio 0
	s_setprio 1
	v_mfma_f32_16x16x32_bf16 v[116:119], v[174:177], v[190:193], v[116:119]
	v_mfma_f32_16x16x32_bf16 v[112:115], v[182:185], v[190:193], v[112:115]
	v_mfma_f32_16x16x32_bf16 v[100:103], v[174:177], v[200:203], v[100:103]
	v_mfma_f32_16x16x32_bf16 v[96:99], v[182:185], v[200:203], v[96:99]
	v_mfma_f32_16x16x32_bf16 v[84:87], v[174:177], v[208:211], v[84:87]
	v_mfma_f32_16x16x32_bf16 v[80:83], v[182:185], v[208:211], v[80:83]
	v_mfma_f32_16x16x32_bf16 v[68:71], v[174:177], v[216:219], v[68:71]
	v_mfma_f32_16x16x32_bf16 v[64:67], v[182:185], v[216:219], v[64:67]
	v_mfma_f32_16x16x32_bf16 v[116:119], v[178:181], v[194:197], v[116:119]
	v_mfma_f32_16x16x32_bf16 v[112:115], v[186:189], v[194:197], v[112:115]
	v_mfma_f32_16x16x32_bf16 v[100:103], v[178:181], v[204:207], v[100:103]
	v_mfma_f32_16x16x32_bf16 v[96:99], v[186:189], v[204:207], v[96:99]
	v_mfma_f32_16x16x32_bf16 v[84:87], v[178:181], v[212:215], v[84:87]
	v_mfma_f32_16x16x32_bf16 v[80:83], v[186:189], v[212:215], v[80:83]
	v_mfma_f32_16x16x32_bf16 v[68:71], v[178:181], v[220:223], v[68:71]
	v_mfma_f32_16x16x32_bf16 v[64:67], v[186:189], v[220:223], v[64:67]
	s_setprio 0
	s_barrier
	s_setprio 2
	s_add_u32 s98, s2, s14
	s_addc_u32 s99, s3, s15
	s_add_u32 s100, s30, s14
	s_addc_u32 s101, s31, s15
	s_add_i32 s59, s48, s33
	s_mov_b32 m0, s59
	ds_read_b128 v[190:193], v160 offset:16384
	ds_read_b128 v[194:197], v160 offset:17408
	ds_read_b128 v[200:203], v160 offset:18432
	ds_read_b128 v[204:207], v160 offset:19456
	ds_read_b128 v[208:211], v160 offset:20480
	ds_read_b128 v[212:215], v160 offset:21504
	ds_read_b128 v[216:219], v160 offset:22528
	ds_read_b128 v[220:223], v160 offset:23552
	global_load_lds_dwordx4 v130, s[2:3]
	s_add_i32 m0, s59, 0x2000
	s_add_u32 s68, s2, 0x80000
	s_addc_u32 s69, s3, 0
	s_add_i32 s59, s49, s33
	global_load_lds_dwordx4 v134, s[2:3]
	s_mov_b32 m0, s59
	s_nop 0
	global_load_lds_dwordx4 v130, s[68:69]
	s_add_i32 m0, s59, 0x2000
	s_nop 0
	global_load_lds_dwordx4 v134, s[68:69]
	s_mov_b32 m0, s34
	s_nop 0
	global_load_lds_dwordx4 v128, s[30:31]
	s_mov_b32 m0, s35
	s_nop 0
	global_load_lds_dwordx4 v132, s[30:31]
	s_waitcnt vmcnt(8)
	s_waitcnt lgkmcnt(0)
	s_barrier
	s_setprio 1
	s_waitcnt lgkmcnt(0)
	v_mfma_f32_16x16x32_bf16 v[60:63], v[144:147], v[190:193], v[60:63]
	v_mfma_f32_16x16x32_bf16 v[56:59], v[166:169], v[190:193], v[56:59]
	v_mfma_f32_16x16x32_bf16 v[44:47], v[144:147], v[200:203], v[44:47]
	v_mfma_f32_16x16x32_bf16 v[40:43], v[166:169], v[200:203], v[40:43]
	v_mfma_f32_16x16x32_bf16 v[28:31], v[144:147], v[208:211], v[28:31]
	v_mfma_f32_16x16x32_bf16 v[24:27], v[166:169], v[208:211], v[24:27]
	v_mfma_f32_16x16x32_bf16 v[12:15], v[144:147], v[216:219], v[12:15]
	v_mfma_f32_16x16x32_bf16 v[8:11], v[166:169], v[216:219], v[8:11]
	v_mfma_f32_16x16x32_bf16 v[60:63], v[162:165], v[194:197], v[60:63]
	v_mfma_f32_16x16x32_bf16 v[56:59], v[170:173], v[194:197], v[56:59]
	v_mfma_f32_16x16x32_bf16 v[44:47], v[162:165], v[204:207], v[44:47]
	v_mfma_f32_16x16x32_bf16 v[40:43], v[170:173], v[204:207], v[40:43]
	v_mfma_f32_16x16x32_bf16 v[28:31], v[162:165], v[212:215], v[28:31]
	v_mfma_f32_16x16x32_bf16 v[24:27], v[170:173], v[212:215], v[24:27]
	v_mfma_f32_16x16x32_bf16 v[12:15], v[162:165], v[220:223], v[12:15]
	v_mfma_f32_16x16x32_bf16 v[8:11], v[170:173], v[220:223], v[8:11]
	s_setprio 0
	s_setprio 1
	v_mfma_f32_16x16x32_bf16 v[52:55], v[174:177], v[190:193], v[52:55]
	v_mfma_f32_16x16x32_bf16 v[48:51], v[182:185], v[190:193], v[48:51]
	v_mfma_f32_16x16x32_bf16 v[36:39], v[174:177], v[200:203], v[36:39]
	v_mfma_f32_16x16x32_bf16 v[32:35], v[182:185], v[200:203], v[32:35]
	v_mfma_f32_16x16x32_bf16 v[20:23], v[174:177], v[208:211], v[20:23]
	v_mfma_f32_16x16x32_bf16 v[16:19], v[182:185], v[208:211], v[16:19]
	v_mfma_f32_16x16x32_bf16 v[4:7], v[174:177], v[216:219], v[4:7]
	v_mfma_f32_16x16x32_bf16 v[0:3], v[182:185], v[216:219], v[0:3]
	v_mfma_f32_16x16x32_bf16 v[52:55], v[178:181], v[194:197], v[52:55]
	v_mfma_f32_16x16x32_bf16 v[48:51], v[186:189], v[194:197], v[48:51]
	v_mfma_f32_16x16x32_bf16 v[36:39], v[178:181], v[204:207], v[36:39]
	v_mfma_f32_16x16x32_bf16 v[32:35], v[186:189], v[204:207], v[32:35]
	v_mfma_f32_16x16x32_bf16 v[20:23], v[178:181], v[212:215], v[20:23]
	v_mfma_f32_16x16x32_bf16 v[16:19], v[186:189], v[212:215], v[16:19]
	v_mfma_f32_16x16x32_bf16 v[4:7], v[178:181], v[220:223], v[4:7]
	v_mfma_f32_16x16x32_bf16 v[0:3], v[186:189], v[220:223], v[0:3]
	s_setprio 0
	s_barrier
; #define PG8_STAGE(bufoff, gbase, voff) do { _Pragma("unroll") for (int _i = 0; _i < 2; ++_i) \
;         __builtin_amdgcn_global_load_lds((const unsigned*)((const char*)(gbase) + (voff)[_i]), (PG8_LAS unsigned*)(lds + (bufoff) + ldsw + _i * 8192), 16, 0, 0); } while (0)
; #define PG8_LDA(dst, b, h) do { _Pragma("unroll") for (int m = 0; m < 4; ++m) _Pragma("unroll") for (int k = 0; k < 2; ++k) dst[m][k] = *(const PG8_LAS bf16x8*)(lds + PG8_SA(b, h) + aoff + m * 2048 + k * 1024); } while (0)
; #define PG8_LDB(dst, b, h) do { _Pragma("unroll") for (int n = 0; n < 2; ++n) _Pragma("unroll") for (int k = 0; k < 2; ++k) dst[n][k] = *(const PG8_LAS bf16x8*)(lds + PG8_SB(b, h) + boff + n * 2048 + k * 1024); } while (0)
; #define PG8_MMA(ai, bj, At, Bt) do { __builtin_amdgcn_s_setprio(1); _Pragma("unroll") for (int m = 0; m < 4; ++m) _Pragma("unroll") for (int n = 0; n < 2; ++n) _Pragma("unroll") for (int k = 0; k < 2; ++k) \
;         acc[ai][bj][m][n] = __builtin_amdgcn_mfma_f32_16x16x32_bf16(Bt[n][k], At[m][k], acc[ai][bj][m][n], 0, 0, 0); __builtin_amdgcn_s_setprio(0); } while (0)
; #define PG8_WAIT_V(n) asm volatile("s_waitcnt vmcnt(" #n ")" ::: "memory")
; #define PG8_WAIT_L(n) asm volatile("s_waitcnt lgkmcnt(" #n ")" ::: "memory")
; #define PG8_BAR __builtin_amdgcn_s_barrier()
; #define PG8_SCHED __builtin_amdgcn_sched_barrier(0)
; template <class Epi, class Sched, bool ALIGN_EPI = false, bool SP2 = false>
; __device__ __forceinline__ void gemm_phase(PG8_LAS unsigned char* lds, const Gemm g, const Sched& S, const Epi& E) {
;     ...
;             PG8_LDB(B0, 1, 0); PG8_LDB(B1, 1, 1); PG8_SCHED; PG8_LDA(At, 1, 0); PG8_STAGE(PG8_SA(0, 1), a2 + hstep, voffA);
;             PG8_WAIT_V(8); PG8_WAIT_L(0); PG8_BAR; PG8_MMA(0, 0, At, B0); PG8_MMA(0, 1, At, B1); PG8_BAR; PG8_SCHED;
;             PG8_LDA(At, 1, 1); PG8_STAGE(PG8_SB(1, 0), b3, voffB); PG8_STAGE(PG8_SB(1, 1), b3 + hstep, voffB); PG8_STAGE(PG8_SA(1, 0), a3, voffA);
;             PG8_WAIT_V(8); PG8_WAIT_L(0); PG8_BAR; PG8_MMA(1, 0, At, B0); PG8_MMA(1, 1, At, B1); PG8_BAR; PG8_SCHED;
;     ...
;         if constexpr (ALIGN_EPI) { if (wr == 0) PG8_BAR; }
;         if constexpr (!Epi::AFTER_DRAIN) { E(acc, cur, wr, wc, fr, fq); S.done(cur); }
;         if (!has_next) break;
	s_setprio 2
	s_add_i32 s59, 0, 0x18000
	v_add_u32_e32 v155, s59, v156
	s_add_i32 s68, 0, 0x1c000
	ds_read_b128 v[144:147], v155
	ds_read_b128 v[162:165], v155 offset:1024
	ds_read_b128 v[166:169], v155 offset:2048
	ds_read_b128 v[170:173], v155 offset:3072
	v_add_u32_e32 v155, s68, v156
	ds_read_b128 v[174:177], v155
	ds_read_b128 v[178:181], v155 offset:1024
	ds_read_b128 v[182:185], v155 offset:2048
	ds_read_b128 v[186:189], v155 offset:3072
	s_add_u32 s30, s30, 0x80000
	s_addc_u32 s31, s31, 0
	s_mov_b32 m0, s36
	ds_read_b128 v[190:193], v160 offset:32768
	ds_read_b128 v[194:197], v160 offset:33792
	ds_read_b128 v[200:203], v160 offset:34816
	ds_read_b128 v[204:207], v160 offset:35840
	ds_read_b128 v[208:211], v160 offset:36864
	ds_read_b128 v[212:215], v160 offset:37888
	ds_read_b128 v[216:219], v160 offset:38912
	ds_read_b128 v[220:223], v160 offset:39936
	global_load_lds_dwordx4 v128, s[30:31]
	s_mov_b32 m0, s37
	s_nop 0
	global_load_lds_dwordx4 v132, s[30:31]
	s_waitcnt vmcnt(8)
	s_waitcnt lgkmcnt(0)
	s_barrier
	s_setprio 1
	s_waitcnt lgkmcnt(0)
	v_mfma_f32_16x16x32_bf16 v[124:127], v[144:147], v[190:193], v[124:127]
	v_mfma_f32_16x16x32_bf16 v[120:123], v[166:169], v[190:193], v[120:123]
	v_mfma_f32_16x16x32_bf16 v[108:111], v[144:147], v[200:203], v[108:111]
	v_mfma_f32_16x16x32_bf16 v[104:107], v[166:169], v[200:203], v[104:107]
	v_mfma_f32_16x16x32_bf16 v[92:95], v[144:147], v[208:211], v[92:95]
	v_mfma_f32_16x16x32_bf16 v[88:91], v[166:169], v[208:211], v[88:91]
	v_mfma_f32_16x16x32_bf16 v[76:79], v[144:147], v[216:219], v[76:79]
	v_mfma_f32_16x16x32_bf16 v[72:75], v[166:169], v[216:219], v[72:75]
	v_mfma_f32_16x16x32_bf16 v[124:127], v[162:165], v[194:197], v[124:127]
	v_mfma_f32_16x16x32_bf16 v[120:123], v[170:173], v[194:197], v[120:123]
	v_mfma_f32_16x16x32_bf16 v[108:111], v[162:165], v[204:207], v[108:111]
	v_mfma_f32_16x16x32_bf16 v[104:107], v[170:173], v[204:207], v[104:107]
	v_mfma_f32_16x16x32_bf16 v[92:95], v[162:165], v[212:215], v[92:95]
	v_mfma_f32_16x16x32_bf16 v[88:91], v[170:173], v[212:215], v[88:91]
	v_mfma_f32_16x16x32_bf16 v[76:79], v[162:165], v[220:223], v[76:79]
	v_mfma_f32_16x16x32_bf16 v[72:75], v[170:173], v[220:223], v[72:75]
	s_setprio 0
	s_setprio 1
	v_mfma_f32_16x16x32_bf16 v[116:119], v[174:177], v[190:193], v[116:119]
	v_mfma_f32_16x16x32_bf16 v[112:115], v[182:185], v[190:193], v[112:115]
	v_mfma_f32_16x16x32_bf16 v[100:103], v[174:177], v[200:203], v[100:103]
	v_mfma_f32_16x16x32_bf16 v[96:99], v[182:185], v[200:203], v[96:99]
	v_mfma_f32_16x16x32_bf16 v[84:87], v[174:177], v[208:211], v[84:87]
	v_mfma_f32_16x16x32_bf16 v[80:83], v[182:185], v[208:211], v[80:83]
	v_mfma_f32_16x16x32_bf16 v[68:71], v[174:177], v[216:219], v[68:71]
	v_mfma_f32_16x16x32_bf16 v[64:67], v[182:185], v[216:219], v[64:67]
	v_mfma_f32_16x16x32_bf16 v[116:119], v[178:181], v[194:197], v[116:119]
	v_mfma_f32_16x16x32_bf16 v[112:115], v[186:189], v[194:197], v[112:115]
	v_mfma_f32_16x16x32_bf16 v[100:103], v[178:181], v[204:207], v[100:103]
	v_mfma_f32_16x16x32_bf16 v[96:99], v[186:189], v[204:207], v[96:99]
	v_mfma_f32_16x16x32_bf16 v[84:87], v[178:181], v[212:215], v[84:87]
	v_mfma_f32_16x16x32_bf16 v[80:83], v[186:189], v[212:215], v[80:83]
	v_mfma_f32_16x16x32_bf16 v[68:71], v[178:181], v[220:223], v[68:71]
	v_mfma_f32_16x16x32_bf16 v[64:67], v[186:189], v[220:223], v[64:67]
	s_setprio 0
	s_barrier
	s_setprio 2
	s_add_i32 s30, s59, s33
	s_mov_b32 m0, s30
	ds_read_b128 v[190:193], v160 offset:49152
	ds_read_b128 v[194:197], v160 offset:50176
	ds_read_b128 v[200:203], v160 offset:51200
	ds_read_b128 v[204:207], v160 offset:52224
	ds_read_b128 v[208:211], v160 offset:53248
	ds_read_b128 v[212:215], v160 offset:54272
	ds_read_b128 v[216:219], v160 offset:55296
	ds_read_b128 v[220:223], v160 offset:56320
	global_load_lds_dwordx4 v130, s[98:99]
	s_add_i32 m0, s30, 0x2000
	s_add_u32 s2, s2, 0x80080
	s_addc_u32 s3, s3, 0
	s_add_i32 s30, s68, s33
	global_load_lds_dwordx4 v134, s[98:99]
	s_mov_b32 m0, s30
	s_nop 0
	global_load_lds_dwordx4 v130, s[2:3]
	s_add_i32 m0, s30, 0x2000
	s_nop 0
	global_load_lds_dwordx4 v134, s[2:3]
	s_mov_b32 m0, s41
	s_nop 0
	global_load_lds_dwordx4 v128, s[100:101]
	s_mov_b32 m0, s42
	s_nop 0
	global_load_lds_dwordx4 v132, s[100:101]
	s_waitcnt vmcnt(8)
	s_waitcnt lgkmcnt(0)
	s_barrier
	s_setprio 1
	s_waitcnt lgkmcnt(0)
	v_mfma_f32_16x16x32_bf16 v[60:63], v[144:147], v[190:193], v[60:63]
	v_mfma_f32_16x16x32_bf16 v[56:59], v[166:169], v[190:193], v[56:59]
	v_mfma_f32_16x16x32_bf16 v[44:47], v[144:147], v[200:203], v[44:47]
	v_mfma_f32_16x16x32_bf16 v[40:43], v[166:169], v[200:203], v[40:43]
	v_mfma_f32_16x16x32_bf16 v[28:31], v[144:147], v[208:211], v[28:31]
	v_mfma_f32_16x16x32_bf16 v[24:27], v[166:169], v[208:211], v[24:27]
	v_mfma_f32_16x16x32_bf16 v[12:15], v[144:147], v[216:219], v[12:15]
	v_mfma_f32_16x16x32_bf16 v[8:11], v[166:169], v[216:219], v[8:11]
	v_mfma_f32_16x16x32_bf16 v[60:63], v[162:165], v[194:197], v[60:63]
	v_mfma_f32_16x16x32_bf16 v[56:59], v[170:173], v[194:197], v[56:59]
	v_mfma_f32_16x16x32_bf16 v[44:47], v[162:165], v[204:207], v[44:47]
	v_mfma_f32_16x16x32_bf16 v[40:43], v[170:173], v[204:207], v[40:43]
	v_mfma_f32_16x16x32_bf16 v[28:31], v[162:165], v[212:215], v[28:31]
	v_mfma_f32_16x16x32_bf16 v[24:27], v[170:173], v[212:215], v[24:27]
	v_mfma_f32_16x16x32_bf16 v[12:15], v[162:165], v[220:223], v[12:15]
	v_mfma_f32_16x16x32_bf16 v[8:11], v[170:173], v[220:223], v[8:11]
	s_setprio 0
	s_setprio 1
	v_mfma_f32_16x16x32_bf16 v[52:55], v[174:177], v[190:193], v[52:55]
	v_mfma_f32_16x16x32_bf16 v[48:51], v[182:185], v[190:193], v[48:51]
	v_mfma_f32_16x16x32_bf16 v[36:39], v[174:177], v[200:203], v[36:39]
	v_mfma_f32_16x16x32_bf16 v[32:35], v[182:185], v[200:203], v[32:35]
	v_mfma_f32_16x16x32_bf16 v[20:23], v[174:177], v[208:211], v[20:23]
	v_mfma_f32_16x16x32_bf16 v[16:19], v[182:185], v[208:211], v[16:19]
	v_mfma_f32_16x16x32_bf16 v[4:7], v[174:177], v[216:219], v[4:7]
	v_mfma_f32_16x16x32_bf16 v[0:3], v[182:185], v[216:219], v[0:3]
	v_mfma_f32_16x16x32_bf16 v[52:55], v[178:181], v[194:197], v[52:55]
	v_mfma_f32_16x16x32_bf16 v[48:51], v[186:189], v[194:197], v[48:51]
	v_mfma_f32_16x16x32_bf16 v[36:39], v[178:181], v[204:207], v[36:39]
	v_mfma_f32_16x16x32_bf16 v[32:35], v[186:189], v[204:207], v[32:35]
	v_mfma_f32_16x16x32_bf16 v[20:23], v[178:181], v[212:215], v[20:23]
	v_mfma_f32_16x16x32_bf16 v[16:19], v[186:189], v[212:215], v[16:19]
	v_mfma_f32_16x16x32_bf16 v[4:7], v[178:181], v[220:223], v[4:7]
	v_mfma_f32_16x16x32_bf16 v[0:3], v[186:189], v[220:223], v[0:3]
	s_setprio 0
	s_barrier
	s_add_i32 s58, s58, 2
	s_add_u32 s28, s28, 0x100
	s_addc_u32 s29, s29, 0
	s_add_u32 s52, s52, 0x100
	s_addc_u32 s53, s53, 0
	s_cmp_gt_u32 s58, 29
	s_cbranch_scc0 .LBB0_527
	s_and_b64 vcc, exec, s[16:17]
	s_cbranch_vccz .LBB0_530
	s_barrier

; #define PG8_STAGE(bufoff, gbase, voff) do { _Pragma("unroll") for (int _i = 0; _i < 2; ++_i) \
;         __builtin_amdgcn_global_load_lds((const unsigned*)((const char*)(gbase) + (voff)[_i]), (PG8_LAS unsigned*)(lds + (bufoff) + ldsw + _i * 8192), 16, 0, 0); } while (0)
; #define PG8_LDA(dst, b, h) do { _Pragma("unroll") for (int m = 0; m < 4; ++m) _Pragma("unroll") for (int k = 0; k < 2; ++k) dst[m][k] = *(const PG8_LAS bf16x8*)(lds + PG8_SA(b, h) + aoff + m * 2048 + k * 1024); } while (0)
; #define PG8_LDB(dst, b, h) do { _Pragma("unroll") for (int n = 0; n < 2; ++n) _Pragma("unroll") for (int k = 0; k < 2; ++k) dst[n][k] = *(const PG8_LAS bf16x8*)(lds + PG8_SB(b, h) + boff + n * 2048 + k * 1024); } while (0)
; #define PG8_MMA(ai, bj, At, Bt) do { __builtin_amdgcn_s_setprio(1); _Pragma("unroll") for (int m = 0; m < 4; ++m) _Pragma("unroll") for (int n = 0; n < 2; ++n) _Pragma("unroll") for (int k = 0; k < 2; ++k) \
;         acc[ai][bj][m][n] = __builtin_amdgcn_mfma_f32_16x16x32_bf16(Bt[n][k], At[m][k], acc[ai][bj][m][n], 0, 0, 0); __builtin_amdgcn_s_setprio(0); } while (0)
; #define PG8_WAIT_V(n) asm volatile("s_waitcnt vmcnt(" #n ")" ::: "memory")
; #define PG8_WAIT_L(n) asm volatile("s_waitcnt lgkmcnt(" #n ")" ::: "memory")
; #define PG8_BAR __builtin_amdgcn_s_barrier()
; template <class Epi, class Sched, bool ALIGN_EPI = false, bool SP2 = false>
; __device__ __forceinline__ void gemm_phase(PG8_LAS unsigned char* lds, const Gemm g, const Sched& S, const Epi& E) {
;     ...
;             const char* a1 = cA + (size_t)(t + 1) * kstep;
;             const char* a2 = last ? nA : cA + (size_t)(t + 2) * kstep; const char* b2 = last ? nB : cB + (size_t)(t + 2) * kstep;
;             const char* a3 = a2 + kstep; const char* b3 = b2 + kstep;
;             if (last && has_next) S.a_ready(nxt);
;             if constexpr (SP2) {
;             PG8_LDB(B0, 0, 0); PG8_LDB(B1, 0, 1); PG8_SCHED; PG8_LDA(At, 0, 0); PG8_STAGE(PG8_SA(1, 1), a1 + hstep, voffA);
;             PG8_WAIT_V(8); PG8_WAIT_L(0); PG8_BAR; PG8_MMA(0, 0, At, B0); PG8_MMA(0, 1, At, B1); PG8_BAR; PG8_SCHED;
;             PG8_LDA(At, 0, 1); PG8_STAGE(PG8_SB(0, 0), b2, voffB); PG8_STAGE(PG8_SB(0, 1), b2 + hstep, voffB); PG8_STAGE(PG8_SA(0, 0), a2, voffA);
;             PG8_WAIT_V(8); PG8_WAIT_L(0); PG8_BAR; PG8_MMA(1, 0, At, B0); PG8_MMA(1, 1, At, B1); PG8_BAR; PG8_SCHED;
.LBB0_629:
	s_setprio 2
	ds_read_b128 v[156:159], v151
	ds_read_b128 v[160:163], v151 offset:1024
	ds_read_b128 v[164:167], v151 offset:2048
	ds_read_b128 v[168:171], v151 offset:3072
	ds_read_b128 v[172:175], v152
	ds_read_b128 v[176:179], v152 offset:1024
	ds_read_b128 v[180:183], v152 offset:2048
	ds_read_b128 v[184:187], v152 offset:3072
	s_add_u32 s2, s30, 0xfff80080
	s_addc_u32 s3, s31, -1
	s_cmp_eq_u32 s58, 28
	s_cselect_b32 s35, s23, s3
	s_cselect_b32 s34, s52, s2
	s_cselect_b32 s3, s21, s57
	s_cselect_b32 s2, s53, s56
	s_add_i32 m0, s29, 0xc000
	ds_read_b128 v[188:191], v153
	ds_read_b128 v[192:195], v153 offset:1024
	ds_read_b128 v[200:203], v153 offset:2048
	ds_read_b128 v[204:207], v153 offset:3072
	ds_read_b128 v[208:211], v153 offset:4096
	ds_read_b128 v[212:215], v153 offset:5120
	ds_read_b128 v[216:219], v153 offset:6144
	ds_read_b128 v[220:223], v153 offset:7168
	global_load_lds_dwordx4 v136, s[30:31]
	s_add_i32 m0, s29, 0xe000
	s_nop 0
	global_load_lds_dwordx4 v138, s[30:31]
	s_waitcnt vmcnt(8)
	s_waitcnt lgkmcnt(0)
	s_barrier
	s_setprio 1
	s_waitcnt lgkmcnt(0)
	v_mfma_f32_16x16x32_bf16 v[124:127], v[156:159], v[188:191], v[124:127]
	v_mfma_f32_16x16x32_bf16 v[120:123], v[164:167], v[188:191], v[120:123]
	v_mfma_f32_16x16x32_bf16 v[108:111], v[156:159], v[200:203], v[108:111]
	v_mfma_f32_16x16x32_bf16 v[104:107], v[164:167], v[200:203], v[104:107]
	v_mfma_f32_16x16x32_bf16 v[92:95], v[156:159], v[208:211], v[92:95]
	v_mfma_f32_16x16x32_bf16 v[88:91], v[164:167], v[208:211], v[88:91]
	v_mfma_f32_16x16x32_bf16 v[76:79], v[156:159], v[216:219], v[76:79]
	v_mfma_f32_16x16x32_bf16 v[72:75], v[164:167], v[216:219], v[72:75]
	v_mfma_f32_16x16x32_bf16 v[124:127], v[160:163], v[192:195], v[124:127]
	v_mfma_f32_16x16x32_bf16 v[120:123], v[168:171], v[192:195], v[120:123]
	v_mfma_f32_16x16x32_bf16 v[108:111], v[160:163], v[204:207], v[108:111]
	v_mfma_f32_16x16x32_bf16 v[104:107], v[168:171], v[204:207], v[104:107]
	v_mfma_f32_16x16x32_bf16 v[92:95], v[160:163], v[212:215], v[92:95]
	v_mfma_f32_16x16x32_bf16 v[88:91], v[168:171], v[212:215], v[88:91]
	v_mfma_f32_16x16x32_bf16 v[76:79], v[160:163], v[220:223], v[76:79]
	v_mfma_f32_16x16x32_bf16 v[72:75], v[168:171], v[220:223], v[72:75]
	s_setprio 0
	s_setprio 1
	v_mfma_f32_16x16x32_bf16 v[116:119], v[172:175], v[188:191], v[116:119]
	v_mfma_f32_16x16x32_bf16 v[112:115], v[180:183], v[188:191], v[112:115]
	v_mfma_f32_16x16x32_bf16 v[100:103], v[172:175], v[200:203], v[100:103]
	v_mfma_f32_16x16x32_bf16 v[96:99], v[180:183], v[200:203], v[96:99]
	v_mfma_f32_16x16x32_bf16 v[84:87], v[172:175], v[208:211], v[84:87]
	v_mfma_f32_16x16x32_bf16 v[80:83], v[180:183], v[208:211], v[80:83]
	v_mfma_f32_16x16x32_bf16 v[68:71], v[172:175], v[216:219], v[68:71]
	v_mfma_f32_16x16x32_bf16 v[64:67], v[180:183], v[216:219], v[64:67]
	v_mfma_f32_16x16x32_bf16 v[116:119], v[176:179], v[192:195], v[116:119]
	v_mfma_f32_16x16x32_bf16 v[112:115], v[184:187], v[192:195], v[112:115]
	v_mfma_f32_16x16x32_bf16 v[100:103], v[176:179], v[204:207], v[100:103]
	v_mfma_f32_16x16x32_bf16 v[96:99], v[184:187], v[204:207], v[96:99]
	v_mfma_f32_16x16x32_bf16 v[84:87], v[176:179], v[212:215], v[84:87]
	v_mfma_f32_16x16x32_bf16 v[80:83], v[184:187], v[212:215], v[80:83]
	v_mfma_f32_16x16x32_bf16 v[68:71], v[176:179], v[220:223], v[68:71]
	v_mfma_f32_16x16x32_bf16 v[64:67], v[184:187], v[220:223], v[64:67]
	s_setprio 0
	s_barrier
	s_setprio 2
	s_add_u32 s98, s2, s8
	s_addc_u32 s99, s3, s9
	s_add_u32 s100, s34, s8
	s_addc_u32 s101, s35, s9
	s_add_i32 s59, s45, s33
	s_mov_b32 m0, s59
	ds_read_b128 v[188:191], v153 offset:16384
	ds_read_b128 v[192:195], v153 offset:17408
	ds_read_b128 v[200:203], v153 offset:18432
	ds_read_b128 v[204:207], v153 offset:19456
	ds_read_b128 v[208:211], v153 offset:20480
	ds_read_b128 v[212:215], v153 offset:21504
	ds_read_b128 v[216:219], v153 offset:22528
	ds_read_b128 v[220:223], v153 offset:23552
	global_load_lds_dwordx4 v130, s[2:3]
	s_add_i32 m0, s59, 0x2000
	s_add_u32 s68, s2, 0x80000
	s_addc_u32 s69, s3, 0
	s_add_i32 s59, s46, s33
	global_load_lds_dwordx4 v134, s[2:3]
	s_mov_b32 m0, s59
	s_nop 0
	global_load_lds_dwordx4 v130, s[68:69]
	s_add_i32 m0, s59, 0x2000
	s_nop 0
	global_load_lds_dwordx4 v134, s[68:69]
	s_mov_b32 m0, s29
	s_nop 0
	global_load_lds_dwordx4 v128, s[34:35]
	s_mov_b32 m0, s37
	s_nop 0
	global_load_lds_dwordx4 v132, s[34:35]
	s_waitcnt vmcnt(8)
	s_waitcnt lgkmcnt(0)
	s_barrier
	s_setprio 1
	s_waitcnt lgkmcnt(0)
	v_mfma_f32_16x16x32_bf16 v[60:63], v[156:159], v[188:191], v[60:63]
	v_mfma_f32_16x16x32_bf16 v[56:59], v[164:167], v[188:191], v[56:59]
	v_mfma_f32_16x16x32_bf16 v[44:47], v[156:159], v[200:203], v[44:47]
	v_mfma_f32_16x16x32_bf16 v[40:43], v[164:167], v[200:203], v[40:43]
	v_mfma_f32_16x16x32_bf16 v[28:31], v[156:159], v[208:211], v[28:31]
	v_mfma_f32_16x16x32_bf16 v[24:27], v[164:167], v[208:211], v[24:27]
	v_mfma_f32_16x16x32_bf16 v[12:15], v[156:159], v[216:219], v[12:15]
	v_mfma_f32_16x16x32_bf16 v[8:11], v[164:167], v[216:219], v[8:11]
	v_mfma_f32_16x16x32_bf16 v[60:63], v[160:163], v[192:195], v[60:63]
	v_mfma_f32_16x16x32_bf16 v[56:59], v[168:171], v[192:195], v[56:59]
	v_mfma_f32_16x16x32_bf16 v[44:47], v[160:163], v[204:207], v[44:47]
	v_mfma_f32_16x16x32_bf16 v[40:43], v[168:171], v[204:207], v[40:43]
	v_mfma_f32_16x16x32_bf16 v[28:31], v[160:163], v[212:215], v[28:31]
	v_mfma_f32_16x16x32_bf16 v[24:27], v[168:171], v[212:215], v[24:27]
	v_mfma_f32_16x16x32_bf16 v[12:15], v[160:163], v[220:223], v[12:15]
	v_mfma_f32_16x16x32_bf16 v[8:11], v[168:171], v[220:223], v[8:11]
	s_setprio 0
	s_setprio 1
	v_mfma_f32_16x16x32_bf16 v[52:55], v[172:175], v[188:191], v[52:55]
	v_mfma_f32_16x16x32_bf16 v[48:51], v[180:183], v[188:191], v[48:51]
	v_mfma_f32_16x16x32_bf16 v[36:39], v[172:175], v[200:203], v[36:39]
	v_mfma_f32_16x16x32_bf16 v[32:35], v[180:183], v[200:203], v[32:35]
	v_mfma_f32_16x16x32_bf16 v[20:23], v[172:175], v[208:211], v[20:23]
	v_mfma_f32_16x16x32_bf16 v[16:19], v[180:183], v[208:211], v[16:19]
	v_mfma_f32_16x16x32_bf16 v[4:7], v[172:175], v[216:219], v[4:7]
	v_mfma_f32_16x16x32_bf16 v[0:3], v[180:183], v[216:219], v[0:3]
	v_mfma_f32_16x16x32_bf16 v[52:55], v[176:179], v[192:195], v[52:55]
	v_mfma_f32_16x16x32_bf16 v[48:51], v[184:187], v[192:195], v[48:51]
	v_mfma_f32_16x16x32_bf16 v[36:39], v[176:179], v[204:207], v[36:39]
	v_mfma_f32_16x16x32_bf16 v[32:35], v[184:187], v[204:207], v[32:35]
	v_mfma_f32_16x16x32_bf16 v[20:23], v[176:179], v[212:215], v[20:23]
	v_mfma_f32_16x16x32_bf16 v[16:19], v[184:187], v[212:215], v[16:19]
	v_mfma_f32_16x16x32_bf16 v[4:7], v[176:179], v[220:223], v[4:7]
	v_mfma_f32_16x16x32_bf16 v[0:3], v[184:187], v[220:223], v[0:3]
	s_setprio 0
	s_barrier
; #define PG8_STAGE(bufoff, gbase, voff) do { _Pragma("unroll") for (int _i = 0; _i < 2; ++_i) \
;         __builtin_amdgcn_global_load_lds((const unsigned*)((const char*)(gbase) + (voff)[_i]), (PG8_LAS unsigned*)(lds + (bufoff) + ldsw + _i * 8192), 16, 0, 0); } while (0)
; #define PG8_LDA(dst, b, h) do { _Pragma("unroll") for (int m = 0; m < 4; ++m) _Pragma("unroll") for (int k = 0; k < 2; ++k) dst[m][k] = *(const PG8_LAS bf16x8*)(lds + PG8_SA(b, h) + aoff + m * 2048 + k * 1024); } while (0)
; #define PG8_LDB(dst, b, h) do { _Pragma("unroll") for (int n = 0; n < 2; ++n) _Pragma("unroll") for (int k = 0; k < 2; ++k) dst[n][k] = *(const PG8_LAS bf16x8*)(lds + PG8_SB(b, h) + boff + n * 2048 + k * 1024); } while (0)
; #define PG8_MMA(ai, bj, At, Bt) do { __builtin_amdgcn_s_setprio(1); _Pragma("unroll") for (int m = 0; m < 4; ++m) _Pragma("unroll") for (int n = 0; n < 2; ++n) _Pragma("unroll") for (int k = 0; k < 2; ++k) \
;         acc[ai][bj][m][n] = __builtin_amdgcn_mfma_f32_16x16x32_bf16(Bt[n][k], At[m][k], acc[ai][bj][m][n], 0, 0, 0); __builtin_amdgcn_s_setprio(0); } while (0)
; #define PG8_WAIT_V(n) asm volatile("s_waitcnt vmcnt(" #n ")" ::: "memory")
; #define PG8_WAIT_L(n) asm volatile("s_waitcnt lgkmcnt(" #n ")" ::: "memory")
; #define PG8_BAR __builtin_amdgcn_s_barrier()
; #define PG8_SCHED __builtin_amdgcn_sched_barrier(0)
; template <class Epi, class Sched, bool ALIGN_EPI = false, bool SP2 = false>
; __device__ __forceinline__ void gemm_phase(PG8_LAS unsigned char* lds, const Gemm g, const Sched& S, const Epi& E) {
;     ...
;             PG8_LDB(B0, 1, 0); PG8_LDB(B1, 1, 1); PG8_SCHED; PG8_LDA(At, 1, 0); PG8_STAGE(PG8_SA(0, 1), a2 + hstep, voffA);
;             PG8_WAIT_V(8); PG8_WAIT_L(0); PG8_BAR; PG8_MMA(0, 0, At, B0); PG8_MMA(0, 1, At, B1); PG8_BAR; PG8_SCHED;
;             PG8_LDA(At, 1, 1); PG8_STAGE(PG8_SB(1, 0), b3, voffB); PG8_STAGE(PG8_SB(1, 1), b3 + hstep, voffB); PG8_STAGE(PG8_SA(1, 0), a3, voffA);
;             PG8_WAIT_V(8); PG8_WAIT_L(0); PG8_BAR; PG8_MMA(1, 0, At, B0); PG8_MMA(1, 1, At, B1); PG8_BAR; PG8_SCHED;
;     ...
;         if constexpr (ALIGN_EPI) { if (wr == 0) PG8_BAR; }
;         if constexpr (!Epi::AFTER_DRAIN) { E(acc, cur, wr, wc, fr, fq); S.done(cur); }
;         if (!has_next) break;
	s_setprio 2
	s_add_i32 s59, 0, 0x18000
	s_add_i32 s68, 0, 0x1c000
	v_add_u32_e32 v168, s59, v149
	v_add_u32_e32 v184, s68, v149
	ds_read_b128 v[156:159], v168
	ds_read_b128 v[160:163], v168 offset:1024
	ds_read_b128 v[164:167], v168 offset:2048
	ds_read_b128 v[168:171], v168 offset:3072
	ds_read_b128 v[172:175], v184
	ds_read_b128 v[176:179], v184 offset:1024
	ds_read_b128 v[180:183], v184 offset:2048
	ds_read_b128 v[184:187], v184 offset:3072
	s_add_u32 s34, s34, 0x80000
	s_addc_u32 s35, s35, 0
	s_mov_b32 m0, s38
	ds_read_b128 v[188:191], v153 offset:32768
	ds_read_b128 v[192:195], v153 offset:33792
	ds_read_b128 v[200:203], v153 offset:34816
	ds_read_b128 v[204:207], v153 offset:35840
	ds_read_b128 v[208:211], v153 offset:36864
	ds_read_b128 v[212:215], v153 offset:37888
	ds_read_b128 v[216:219], v153 offset:38912
	ds_read_b128 v[220:223], v153 offset:39936
	global_load_lds_dwordx4 v128, s[34:35]
	s_mov_b32 m0, s39
	s_nop 0
	global_load_lds_dwordx4 v132, s[34:35]
	s_waitcnt vmcnt(8)
	s_waitcnt lgkmcnt(0)
	s_barrier
	s_setprio 1
	s_waitcnt lgkmcnt(0)
	v_mfma_f32_16x16x32_bf16 v[124:127], v[156:159], v[188:191], v[124:127]
	v_mfma_f32_16x16x32_bf16 v[120:123], v[164:167], v[188:191], v[120:123]
	v_mfma_f32_16x16x32_bf16 v[108:111], v[156:159], v[200:203], v[108:111]
	v_mfma_f32_16x16x32_bf16 v[104:107], v[164:167], v[200:203], v[104:107]
	v_mfma_f32_16x16x32_bf16 v[92:95], v[156:159], v[208:211], v[92:95]
	v_mfma_f32_16x16x32_bf16 v[88:91], v[164:167], v[208:211], v[88:91]
	v_mfma_f32_16x16x32_bf16 v[76:79], v[156:159], v[216:219], v[76:79]
	v_mfma_f32_16x16x32_bf16 v[72:75], v[164:167], v[216:219], v[72:75]
	v_mfma_f32_16x16x32_bf16 v[124:127], v[160:163], v[192:195], v[124:127]
	v_mfma_f32_16x16x32_bf16 v[120:123], v[168:171], v[192:195], v[120:123]
	v_mfma_f32_16x16x32_bf16 v[108:111], v[160:163], v[204:207], v[108:111]
	v_mfma_f32_16x16x32_bf16 v[104:107], v[168:171], v[204:207], v[104:107]
	v_mfma_f32_16x16x32_bf16 v[92:95], v[160:163], v[212:215], v[92:95]
	v_mfma_f32_16x16x32_bf16 v[88:91], v[168:171], v[212:215], v[88:91]
	v_mfma_f32_16x16x32_bf16 v[76:79], v[160:163], v[220:223], v[76:79]
	v_mfma_f32_16x16x32_bf16 v[72:75], v[168:171], v[220:223], v[72:75]
	s_setprio 0
	s_setprio 1
	v_mfma_f32_16x16x32_bf16 v[116:119], v[172:175], v[188:191], v[116:119]
	v_mfma_f32_16x16x32_bf16 v[112:115], v[180:183], v[188:191], v[112:115]
	v_mfma_f32_16x16x32_bf16 v[100:103], v[172:175], v[200:203], v[100:103]
	v_mfma_f32_16x16x32_bf16 v[96:99], v[180:183], v[200:203], v[96:99]
	v_mfma_f32_16x16x32_bf16 v[84:87], v[172:175], v[208:211], v[84:87]
	v_mfma_f32_16x16x32_bf16 v[80:83], v[180:183], v[208:211], v[80:83]
	v_mfma_f32_16x16x32_bf16 v[68:71], v[172:175], v[216:219], v[68:71]
	v_mfma_f32_16x16x32_bf16 v[64:67], v[180:183], v[216:219], v[64:67]
	v_mfma_f32_16x16x32_bf16 v[116:119], v[176:179], v[192:195], v[116:119]
	v_mfma_f32_16x16x32_bf16 v[112:115], v[184:187], v[192:195], v[112:115]
	v_mfma_f32_16x16x32_bf16 v[100:103], v[176:179], v[204:207], v[100:103]
	v_mfma_f32_16x16x32_bf16 v[96:99], v[184:187], v[204:207], v[96:99]
	v_mfma_f32_16x16x32_bf16 v[84:87], v[176:179], v[212:215], v[84:87]
	v_mfma_f32_16x16x32_bf16 v[80:83], v[184:187], v[212:215], v[80:83]
	v_mfma_f32_16x16x32_bf16 v[68:71], v[176:179], v[220:223], v[68:71]
	v_mfma_f32_16x16x32_bf16 v[64:67], v[184:187], v[220:223], v[64:67]
	s_setprio 0
	s_barrier
	s_setprio 2
	s_add_i32 s34, s59, s33
	s_mov_b32 m0, s34
	ds_read_b128 v[188:191], v153 offset:49152
	ds_read_b128 v[192:195], v153 offset:50176
	ds_read_b128 v[200:203], v153 offset:51200
	ds_read_b128 v[204:207], v153 offset:52224
	ds_read_b128 v[208:211], v153 offset:53248
	ds_read_b128 v[212:215], v153 offset:54272
	ds_read_b128 v[216:219], v153 offset:55296
	ds_read_b128 v[220:223], v153 offset:56320
	global_load_lds_dwordx4 v130, s[98:99]
	s_add_i32 m0, s34, 0x2000
	s_add_u32 s2, s2, 0x80080
	s_addc_u32 s3, s3, 0
	s_add_i32 s34, s68, s33
	global_load_lds_dwordx4 v134, s[98:99]
	s_mov_b32 m0, s34
	s_nop 0
	global_load_lds_dwordx4 v130, s[2:3]
	s_add_i32 m0, s34, 0x2000
	s_nop 0
	global_load_lds_dwordx4 v134, s[2:3]
	s_mov_b32 m0, s42
	s_nop 0
	global_load_lds_dwordx4 v128, s[100:101]
	s_mov_b32 m0, s43
	s_nop 0
	global_load_lds_dwordx4 v132, s[100:101]
	s_waitcnt vmcnt(8)
	s_waitcnt lgkmcnt(0)
	s_barrier
	s_setprio 1
	s_waitcnt lgkmcnt(0)
	v_mfma_f32_16x16x32_bf16 v[60:63], v[156:159], v[188:191], v[60:63]
	v_mfma_f32_16x16x32_bf16 v[56:59], v[164:167], v[188:191], v[56:59]
	v_mfma_f32_16x16x32_bf16 v[44:47], v[156:159], v[200:203], v[44:47]
	v_mfma_f32_16x16x32_bf16 v[40:43], v[164:167], v[200:203], v[40:43]
	v_mfma_f32_16x16x32_bf16 v[28:31], v[156:159], v[208:211], v[28:31]
	v_mfma_f32_16x16x32_bf16 v[24:27], v[164:167], v[208:211], v[24:27]
	v_mfma_f32_16x16x32_bf16 v[12:15], v[156:159], v[216:219], v[12:15]
	v_mfma_f32_16x16x32_bf16 v[8:11], v[164:167], v[216:219], v[8:11]
	v_mfma_f32_16x16x32_bf16 v[60:63], v[160:163], v[192:195], v[60:63]
	v_mfma_f32_16x16x32_bf16 v[56:59], v[168:171], v[192:195], v[56:59]
	v_mfma_f32_16x16x32_bf16 v[44:47], v[160:163], v[204:207], v[44:47]
	v_mfma_f32_16x16x32_bf16 v[40:43], v[168:171], v[204:207], v[40:43]
	v_mfma_f32_16x16x32_bf16 v[28:31], v[160:163], v[212:215], v[28:31]
	v_mfma_f32_16x16x32_bf16 v[24:27], v[168:171], v[212:215], v[24:27]
	v_mfma_f32_16x16x32_bf16 v[12:15], v[160:163], v[220:223], v[12:15]
	v_mfma_f32_16x16x32_bf16 v[8:11], v[168:171], v[220:223], v[8:11]
	s_setprio 0
	s_setprio 1
	v_mfma_f32_16x16x32_bf16 v[52:55], v[172:175], v[188:191], v[52:55]
	v_mfma_f32_16x16x32_bf16 v[48:51], v[180:183], v[188:191], v[48:51]
	v_mfma_f32_16x16x32_bf16 v[36:39], v[172:175], v[200:203], v[36:39]
	v_mfma_f32_16x16x32_bf16 v[32:35], v[180:183], v[200:203], v[32:35]
	v_mfma_f32_16x16x32_bf16 v[20:23], v[172:175], v[208:211], v[20:23]
	v_mfma_f32_16x16x32_bf16 v[16:19], v[180:183], v[208:211], v[16:19]
	v_mfma_f32_16x16x32_bf16 v[4:7], v[172:175], v[216:219], v[4:7]
	v_mfma_f32_16x16x32_bf16 v[0:3], v[180:183], v[216:219], v[0:3]
	v_mfma_f32_16x16x32_bf16 v[52:55], v[176:179], v[192:195], v[52:55]
	v_mfma_f32_16x16x32_bf16 v[48:51], v[184:187], v[192:195], v[48:51]
	v_mfma_f32_16x16x32_bf16 v[36:39], v[176:179], v[204:207], v[36:39]
	v_mfma_f32_16x16x32_bf16 v[32:35], v[184:187], v[204:207], v[32:35]
	v_mfma_f32_16x16x32_bf16 v[20:23], v[176:179], v[212:215], v[20:23]
	v_mfma_f32_16x16x32_bf16 v[16:19], v[184:187], v[212:215], v[16:19]
	v_mfma_f32_16x16x32_bf16 v[4:7], v[176:179], v[220:223], v[4:7]
	v_mfma_f32_16x16x32_bf16 v[0:3], v[184:187], v[220:223], v[0:3]
	s_setprio 0
	s_barrier
	s_add_i32 s58, s58, 2
	s_add_u32 s30, s30, 0x100
	s_addc_u32 s31, s31, 0
	s_add_u32 s56, s56, 0x100
	s_addc_u32 s57, s57, 0
	s_cmp_gt_u32 s58, 29
	s_cbranch_scc0 .LBB0_629
	s_and_b64 vcc, exec, s[10:11]
	s_cbranch_vccz .LBB0_632
	s_barrier

; #define PG8_STAGE(bufoff, gbase, voff) do { _Pragma("unroll") for (int _i = 0; _i < 2; ++_i) \
;         __builtin_amdgcn_global_load_lds((const unsigned*)((const char*)(gbase) + (voff)[_i]), (PG8_LAS unsigned*)(lds + (bufoff) + ldsw + _i * 8192), 16, 0, 0); } while (0)
; #define PG8_LDA(dst, b, h) do { _Pragma("unroll") for (int m = 0; m < 4; ++m) _Pragma("unroll") for (int k = 0; k < 2; ++k) dst[m][k] = *(const PG8_LAS bf16x8*)(lds + PG8_SA(b, h) + aoff + m * 2048 + k * 1024); } while (0)
; #define PG8_LDB(dst, b, h) do { _Pragma("unroll") for (int n = 0; n < 2; ++n) _Pragma("unroll") for (int k = 0; k < 2; ++k) dst[n][k] = *(const PG8_LAS bf16x8*)(lds + PG8_SB(b, h) + boff + n * 2048 + k * 1024); } while (0)
; #define PG8_MMA(ai, bj, At, Bt) do { __builtin_amdgcn_s_setprio(1); _Pragma("unroll") for (int m = 0; m < 4; ++m) _Pragma("unroll") for (int n = 0; n < 2; ++n) _Pragma("unroll") for (int k = 0; k < 2; ++k) \
;         acc[ai][bj][m][n] = __builtin_amdgcn_mfma_f32_16x16x32_bf16(Bt[n][k], At[m][k], acc[ai][bj][m][n], 0, 0, 0); __builtin_amdgcn_s_setprio(0); } while (0)
; #define PG8_WAIT_V(n) asm volatile("s_waitcnt vmcnt(" #n ")" ::: "memory")
; #define PG8_WAIT_L(n) asm volatile("s_waitcnt lgkmcnt(" #n ")" ::: "memory")
; #define PG8_BAR __builtin_amdgcn_s_barrier()
; template <class Epi, class Sched, bool ALIGN_EPI = false, bool SP2 = false>
; __device__ __forceinline__ void gemm_phase(PG8_LAS unsigned char* lds, const Gemm g, const Sched& S, const Epi& E) {
;     ...
;             const char* a1 = cA + (size_t)(t + 1) * kstep;
;             const char* a2 = last ? nA : cA + (size_t)(t + 2) * kstep; const char* b2 = last ? nB : cB + (size_t)(t + 2) * kstep;
;             const char* a3 = a2 + kstep; const char* b3 = b2 + kstep;
;             if (last && has_next) S.a_ready(nxt);
;             if constexpr (SP2) {
;             PG8_LDB(B0, 0, 0); PG8_LDB(B1, 0, 1); PG8_SCHED; PG8_LDA(At, 0, 0); PG8_STAGE(PG8_SA(1, 1), a1 + hstep, voffA);
;             PG8_WAIT_V(8); PG8_WAIT_L(0); PG8_BAR; PG8_MMA(0, 0, At, B0); PG8_MMA(0, 1, At, B1); PG8_BAR; PG8_SCHED;
;             PG8_LDA(At, 0, 1); PG8_STAGE(PG8_SB(0, 0), b2, voffB); PG8_STAGE(PG8_SB(0, 1), b2 + hstep, voffB); PG8_STAGE(PG8_SA(0, 0), a2, voffA);
;             PG8_WAIT_V(8); PG8_WAIT_L(0); PG8_BAR; PG8_MMA(1, 0, At, B0); PG8_MMA(1, 1, At, B1); PG8_BAR; PG8_SCHED;
.LBB0_717:
	s_setprio 2
	ds_read_b128 v[150:153], v158
	ds_read_b128 v[162:165], v158 offset:1024
	ds_read_b128 v[166:169], v158 offset:2048
	ds_read_b128 v[170:173], v158 offset:3072
	ds_read_b128 v[174:177], v159
	ds_read_b128 v[178:181], v159 offset:1024
	ds_read_b128 v[182:185], v159 offset:2048
	ds_read_b128 v[186:189], v159 offset:3072
	s_add_u32 s2, s28, 0xffe00080
	s_addc_u32 s3, s29, -1
	s_cmpk_eq_i32 s50, 0x7c
	s_cselect_b32 s31, s21, s3
	s_cselect_b32 s30, s46, s2
	s_cselect_b32 s3, s19, s49
	s_cselect_b32 s2, s47, s48
	s_add_i32 m0, s27, 0xc000
	ds_read_b128 v[190:193], v160
	ds_read_b128 v[194:197], v160 offset:1024
	ds_read_b128 v[198:201], v160 offset:2048
	ds_read_b128 v[202:205], v160 offset:3072
	ds_read_b128 v[206:209], v160 offset:4096
	ds_read_b128 v[210:213], v160 offset:5120
	ds_read_b128 v[214:217], v160 offset:6144
	ds_read_b128 v[218:221], v160 offset:7168
	global_load_lds_dwordx4 v142, s[28:29]
	s_add_i32 m0, s27, 0xe000
	s_nop 0
	global_load_lds_dwordx4 v144, s[28:29]
	s_waitcnt vmcnt(8)
	s_waitcnt lgkmcnt(0)
	s_barrier
	s_setprio 1
	s_waitcnt lgkmcnt(0)
	v_mfma_f32_16x16x32_bf16 v[124:127], v[150:153], v[190:193], v[124:127]
	v_mfma_f32_16x16x32_bf16 v[120:123], v[166:169], v[190:193], v[120:123]
	v_mfma_f32_16x16x32_bf16 v[108:111], v[150:153], v[198:201], v[108:111]
	v_mfma_f32_16x16x32_bf16 v[104:107], v[166:169], v[198:201], v[104:107]
	v_mfma_f32_16x16x32_bf16 v[92:95], v[150:153], v[206:209], v[92:95]
	v_mfma_f32_16x16x32_bf16 v[88:91], v[166:169], v[206:209], v[88:91]
	v_mfma_f32_16x16x32_bf16 v[76:79], v[150:153], v[214:217], v[76:79]
	v_mfma_f32_16x16x32_bf16 v[72:75], v[166:169], v[214:217], v[72:75]
	v_mfma_f32_16x16x32_bf16 v[124:127], v[162:165], v[194:197], v[124:127]
	v_mfma_f32_16x16x32_bf16 v[120:123], v[170:173], v[194:197], v[120:123]
	v_mfma_f32_16x16x32_bf16 v[108:111], v[162:165], v[202:205], v[108:111]
	v_mfma_f32_16x16x32_bf16 v[104:107], v[170:173], v[202:205], v[104:107]
	v_mfma_f32_16x16x32_bf16 v[92:95], v[162:165], v[210:213], v[92:95]
	v_mfma_f32_16x16x32_bf16 v[88:91], v[170:173], v[210:213], v[88:91]
	v_mfma_f32_16x16x32_bf16 v[76:79], v[162:165], v[218:221], v[76:79]
	v_mfma_f32_16x16x32_bf16 v[72:75], v[170:173], v[218:221], v[72:75]
	s_setprio 0
	s_setprio 1
	v_mfma_f32_16x16x32_bf16 v[116:119], v[174:177], v[190:193], v[116:119]
	v_mfma_f32_16x16x32_bf16 v[112:115], v[182:185], v[190:193], v[112:115]
	v_mfma_f32_16x16x32_bf16 v[100:103], v[174:177], v[198:201], v[100:103]
	v_mfma_f32_16x16x32_bf16 v[96:99], v[182:185], v[198:201], v[96:99]
	v_mfma_f32_16x16x32_bf16 v[84:87], v[174:177], v[206:209], v[84:87]
	v_mfma_f32_16x16x32_bf16 v[80:83], v[182:185], v[206:209], v[80:83]
	v_mfma_f32_16x16x32_bf16 v[68:71], v[174:177], v[214:217], v[68:71]
	v_mfma_f32_16x16x32_bf16 v[64:67], v[182:185], v[214:217], v[64:67]
	v_mfma_f32_16x16x32_bf16 v[116:119], v[178:181], v[194:197], v[116:119]
	v_mfma_f32_16x16x32_bf16 v[112:115], v[186:189], v[194:197], v[112:115]
	v_mfma_f32_16x16x32_bf16 v[100:103], v[178:181], v[202:205], v[100:103]
	v_mfma_f32_16x16x32_bf16 v[96:99], v[186:189], v[202:205], v[96:99]
	v_mfma_f32_16x16x32_bf16 v[84:87], v[178:181], v[210:213], v[84:87]
	v_mfma_f32_16x16x32_bf16 v[80:83], v[186:189], v[210:213], v[80:83]
	v_mfma_f32_16x16x32_bf16 v[68:71], v[178:181], v[218:221], v[68:71]
	v_mfma_f32_16x16x32_bf16 v[64:67], v[186:189], v[218:221], v[64:67]
	s_setprio 0
	s_barrier
	s_setprio 2
	s_add_u32 s98, s2, s14
	s_addc_u32 s99, s3, s15
	s_add_u32 s100, s30, s14
	s_addc_u32 s101, s31, s15
	s_add_i32 s51, s43, s34
	s_mov_b32 m0, s51
	ds_read_b128 v[190:193], v160 offset:16384
	ds_read_b128 v[194:197], v160 offset:17408
	ds_read_b128 v[198:201], v160 offset:18432
	ds_read_b128 v[202:205], v160 offset:19456
	ds_read_b128 v[206:209], v160 offset:20480
	ds_read_b128 v[210:213], v160 offset:21504
	ds_read_b128 v[214:217], v160 offset:22528
	ds_read_b128 v[218:221], v160 offset:23552
	global_load_lds_dwordx4 v134, s[2:3]
	s_add_i32 m0, s51, 0x2000
	s_add_u32 s52, s2, 0x200000
	s_addc_u32 s53, s3, 0
	s_add_i32 s51, s44, s34
	global_load_lds_dwordx4 v138, s[2:3]
	s_mov_b32 m0, s51
	s_nop 0
	global_load_lds_dwordx4 v134, s[52:53]
	s_add_i32 m0, s51, 0x2000
	s_nop 0
	global_load_lds_dwordx4 v138, s[52:53]
	s_mov_b32 m0, s27
	s_nop 0
	global_load_lds_dwordx4 v132, s[30:31]
	s_mov_b32 m0, s35
	s_nop 0
	global_load_lds_dwordx4 v136, s[30:31]
	s_waitcnt vmcnt(8)
	s_waitcnt lgkmcnt(0)
	s_barrier
	s_setprio 1
	s_waitcnt lgkmcnt(0)
	v_mfma_f32_16x16x32_bf16 v[60:63], v[150:153], v[190:193], v[60:63]
	v_mfma_f32_16x16x32_bf16 v[56:59], v[166:169], v[190:193], v[56:59]
	v_mfma_f32_16x16x32_bf16 v[44:47], v[150:153], v[198:201], v[44:47]
	v_mfma_f32_16x16x32_bf16 v[40:43], v[166:169], v[198:201], v[40:43]
	v_mfma_f32_16x16x32_bf16 v[28:31], v[150:153], v[206:209], v[28:31]
	v_mfma_f32_16x16x32_bf16 v[24:27], v[166:169], v[206:209], v[24:27]
	v_mfma_f32_16x16x32_bf16 v[12:15], v[150:153], v[214:217], v[12:15]
	v_mfma_f32_16x16x32_bf16 v[8:11], v[166:169], v[214:217], v[8:11]
	v_mfma_f32_16x16x32_bf16 v[60:63], v[162:165], v[194:197], v[60:63]
	v_mfma_f32_16x16x32_bf16 v[56:59], v[170:173], v[194:197], v[56:59]
	v_mfma_f32_16x16x32_bf16 v[44:47], v[162:165], v[202:205], v[44:47]
	v_mfma_f32_16x16x32_bf16 v[40:43], v[170:173], v[202:205], v[40:43]
	v_mfma_f32_16x16x32_bf16 v[28:31], v[162:165], v[210:213], v[28:31]
	v_mfma_f32_16x16x32_bf16 v[24:27], v[170:173], v[210:213], v[24:27]
	v_mfma_f32_16x16x32_bf16 v[12:15], v[162:165], v[218:221], v[12:15]
	v_mfma_f32_16x16x32_bf16 v[8:11], v[170:173], v[218:221], v[8:11]
	s_setprio 0
	s_setprio 1
	v_mfma_f32_16x16x32_bf16 v[52:55], v[174:177], v[190:193], v[52:55]
	v_mfma_f32_16x16x32_bf16 v[48:51], v[182:185], v[190:193], v[48:51]
	v_mfma_f32_16x16x32_bf16 v[36:39], v[174:177], v[198:201], v[36:39]
	v_mfma_f32_16x16x32_bf16 v[32:35], v[182:185], v[198:201], v[32:35]
	v_mfma_f32_16x16x32_bf16 v[20:23], v[174:177], v[206:209], v[20:23]
	v_mfma_f32_16x16x32_bf16 v[16:19], v[182:185], v[206:209], v[16:19]
	v_mfma_f32_16x16x32_bf16 v[4:7], v[174:177], v[214:217], v[4:7]
	v_mfma_f32_16x16x32_bf16 v[0:3], v[182:185], v[214:217], v[0:3]
	v_mfma_f32_16x16x32_bf16 v[52:55], v[178:181], v[194:197], v[52:55]
	v_mfma_f32_16x16x32_bf16 v[48:51], v[186:189], v[194:197], v[48:51]
	v_mfma_f32_16x16x32_bf16 v[36:39], v[178:181], v[202:205], v[36:39]
	v_mfma_f32_16x16x32_bf16 v[32:35], v[186:189], v[202:205], v[32:35]
	v_mfma_f32_16x16x32_bf16 v[20:23], v[178:181], v[210:213], v[20:23]
	v_mfma_f32_16x16x32_bf16 v[16:19], v[186:189], v[210:213], v[16:19]
	v_mfma_f32_16x16x32_bf16 v[4:7], v[178:181], v[218:221], v[4:7]
	v_mfma_f32_16x16x32_bf16 v[0:3], v[186:189], v[218:221], v[0:3]
	s_setprio 0
	s_barrier
; #define PG8_STAGE(bufoff, gbase, voff) do { _Pragma("unroll") for (int _i = 0; _i < 2; ++_i) \
;         __builtin_amdgcn_global_load_lds((const unsigned*)((const char*)(gbase) + (voff)[_i]), (PG8_LAS unsigned*)(lds + (bufoff) + ldsw + _i * 8192), 16, 0, 0); } while (0)
; #define PG8_LDA(dst, b, h) do { _Pragma("unroll") for (int m = 0; m < 4; ++m) _Pragma("unroll") for (int k = 0; k < 2; ++k) dst[m][k] = *(const PG8_LAS bf16x8*)(lds + PG8_SA(b, h) + aoff + m * 2048 + k * 1024); } while (0)
; #define PG8_LDB(dst, b, h) do { _Pragma("unroll") for (int n = 0; n < 2; ++n) _Pragma("unroll") for (int k = 0; k < 2; ++k) dst[n][k] = *(const PG8_LAS bf16x8*)(lds + PG8_SB(b, h) + boff + n * 2048 + k * 1024); } while (0)
; #define PG8_MMA(ai, bj, At, Bt) do { __builtin_amdgcn_s_setprio(1); _Pragma("unroll") for (int m = 0; m < 4; ++m) _Pragma("unroll") for (int n = 0; n < 2; ++n) _Pragma("unroll") for (int k = 0; k < 2; ++k) \
;         acc[ai][bj][m][n] = __builtin_amdgcn_mfma_f32_16x16x32_bf16(Bt[n][k], At[m][k], acc[ai][bj][m][n], 0, 0, 0); __builtin_amdgcn_s_setprio(0); } while (0)
; #define PG8_WAIT_V(n) asm volatile("s_waitcnt vmcnt(" #n ")" ::: "memory")
; #define PG8_WAIT_L(n) asm volatile("s_waitcnt lgkmcnt(" #n ")" ::: "memory")
; #define PG8_BAR __builtin_amdgcn_s_barrier()
; #define PG8_SCHED __builtin_amdgcn_sched_barrier(0)
; template <class Epi, class Sched, bool ALIGN_EPI = false, bool SP2 = false>
; __device__ __forceinline__ void gemm_phase(PG8_LAS unsigned char* lds, const Gemm g, const Sched& S, const Epi& E) {
;     ...
;             PG8_LDB(B0, 1, 0); PG8_LDB(B1, 1, 1); PG8_SCHED; PG8_LDA(At, 1, 0); PG8_STAGE(PG8_SA(0, 1), a2 + hstep, voffA);
;             PG8_WAIT_V(8); PG8_WAIT_L(0); PG8_BAR; PG8_MMA(0, 0, At, B0); PG8_MMA(0, 1, At, B1); PG8_BAR; PG8_SCHED;
;             PG8_LDA(At, 1, 1); PG8_STAGE(PG8_SB(1, 0), b3, voffB); PG8_STAGE(PG8_SB(1, 1), b3 + hstep, voffB); PG8_STAGE(PG8_SA(1, 0), a3, voffA);
;             PG8_WAIT_V(8); PG8_WAIT_L(0); PG8_BAR; PG8_MMA(1, 0, At, B0); PG8_MMA(1, 1, At, B1); PG8_BAR; PG8_SCHED;
;     ...
;         if constexpr (ALIGN_EPI) { if (wr == 0) PG8_BAR; }
;         if constexpr (!Epi::AFTER_DRAIN) { E(acc, cur, wr, wc, fr, fq); S.done(cur); }
;         if (!has_next) break;
	s_setprio 2
	s_add_i32 s51, 0, 0x18000
	v_add_u32_e32 v155, s51, v157
	s_add_i32 s52, 0, 0x1c000
	ds_read_b128 v[150:153], v155
	ds_read_b128 v[162:165], v155 offset:1024
	ds_read_b128 v[166:169], v155 offset:2048
	ds_read_b128 v[170:173], v155 offset:3072
	v_add_u32_e32 v155, s52, v157
	ds_read_b128 v[174:177], v155
	ds_read_b128 v[178:181], v155 offset:1024
	ds_read_b128 v[182:185], v155 offset:2048
	ds_read_b128 v[186:189], v155 offset:3072
	s_add_u32 s30, s30, 0x200000
	s_addc_u32 s31, s31, 0
	s_mov_b32 m0, s36
	ds_read_b128 v[190:193], v160 offset:32768
	ds_read_b128 v[194:197], v160 offset:33792
	ds_read_b128 v[198:201], v160 offset:34816
	ds_read_b128 v[202:205], v160 offset:35840
	ds_read_b128 v[206:209], v160 offset:36864
	ds_read_b128 v[210:213], v160 offset:37888
	ds_read_b128 v[214:217], v160 offset:38912
	ds_read_b128 v[218:221], v160 offset:39936
	global_load_lds_dwordx4 v132, s[30:31]
	s_mov_b32 m0, s37
	s_nop 0
	global_load_lds_dwordx4 v136, s[30:31]
	s_waitcnt vmcnt(8)
	s_waitcnt lgkmcnt(0)
	s_barrier
	s_setprio 1
	s_waitcnt lgkmcnt(0)
	v_mfma_f32_16x16x32_bf16 v[124:127], v[150:153], v[190:193], v[124:127]
	v_mfma_f32_16x16x32_bf16 v[120:123], v[166:169], v[190:193], v[120:123]
	v_mfma_f32_16x16x32_bf16 v[108:111], v[150:153], v[198:201], v[108:111]
	v_mfma_f32_16x16x32_bf16 v[104:107], v[166:169], v[198:201], v[104:107]
	v_mfma_f32_16x16x32_bf16 v[92:95], v[150:153], v[206:209], v[92:95]
	v_mfma_f32_16x16x32_bf16 v[88:91], v[166:169], v[206:209], v[88:91]
	v_mfma_f32_16x16x32_bf16 v[76:79], v[150:153], v[214:217], v[76:79]
	v_mfma_f32_16x16x32_bf16 v[72:75], v[166:169], v[214:217], v[72:75]
	v_mfma_f32_16x16x32_bf16 v[124:127], v[162:165], v[194:197], v[124:127]
	v_mfma_f32_16x16x32_bf16 v[120:123], v[170:173], v[194:197], v[120:123]
	v_mfma_f32_16x16x32_bf16 v[108:111], v[162:165], v[202:205], v[108:111]
	v_mfma_f32_16x16x32_bf16 v[104:107], v[170:173], v[202:205], v[104:107]
	v_mfma_f32_16x16x32_bf16 v[92:95], v[162:165], v[210:213], v[92:95]
	v_mfma_f32_16x16x32_bf16 v[88:91], v[170:173], v[210:213], v[88:91]
	v_mfma_f32_16x16x32_bf16 v[76:79], v[162:165], v[218:221], v[76:79]
	v_mfma_f32_16x16x32_bf16 v[72:75], v[170:173], v[218:221], v[72:75]
	s_setprio 0
	s_setprio 1
	v_mfma_f32_16x16x32_bf16 v[116:119], v[174:177], v[190:193], v[116:119]
	v_mfma_f32_16x16x32_bf16 v[112:115], v[182:185], v[190:193], v[112:115]
	v_mfma_f32_16x16x32_bf16 v[100:103], v[174:177], v[198:201], v[100:103]
	v_mfma_f32_16x16x32_bf16 v[96:99], v[182:185], v[198:201], v[96:99]
	v_mfma_f32_16x16x32_bf16 v[84:87], v[174:177], v[206:209], v[84:87]
	v_mfma_f32_16x16x32_bf16 v[80:83], v[182:185], v[206:209], v[80:83]
	v_mfma_f32_16x16x32_bf16 v[68:71], v[174:177], v[214:217], v[68:71]
	v_mfma_f32_16x16x32_bf16 v[64:67], v[182:185], v[214:217], v[64:67]
	v_mfma_f32_16x16x32_bf16 v[116:119], v[178:181], v[194:197], v[116:119]
	v_mfma_f32_16x16x32_bf16 v[112:115], v[186:189], v[194:197], v[112:115]
	v_mfma_f32_16x16x32_bf16 v[100:103], v[178:181], v[202:205], v[100:103]
	v_mfma_f32_16x16x32_bf16 v[96:99], v[186:189], v[202:205], v[96:99]
	v_mfma_f32_16x16x32_bf16 v[84:87], v[178:181], v[210:213], v[84:87]
	v_mfma_f32_16x16x32_bf16 v[80:83], v[186:189], v[210:213], v[80:83]
	v_mfma_f32_16x16x32_bf16 v[68:71], v[178:181], v[218:221], v[68:71]
	v_mfma_f32_16x16x32_bf16 v[64:67], v[186:189], v[218:221], v[64:67]
	s_setprio 0
	s_barrier
	s_setprio 2
	s_add_i32 s30, s51, s34
	s_mov_b32 m0, s30
	ds_read_b128 v[190:193], v160 offset:49152
	ds_read_b128 v[194:197], v160 offset:50176
	ds_read_b128 v[198:201], v160 offset:51200
	ds_read_b128 v[202:205], v160 offset:52224
	ds_read_b128 v[206:209], v160 offset:53248
	ds_read_b128 v[210:213], v160 offset:54272
	ds_read_b128 v[214:217], v160 offset:55296
	ds_read_b128 v[218:221], v160 offset:56320
	global_load_lds_dwordx4 v134, s[98:99]
	s_add_i32 m0, s30, 0x2000
	s_add_u32 s2, s2, 0x200080
	s_addc_u32 s3, s3, 0
	s_add_i32 s30, s52, s34
	global_load_lds_dwordx4 v138, s[98:99]
	s_mov_b32 m0, s30
	s_nop 0
	global_load_lds_dwordx4 v134, s[2:3]
	s_add_i32 m0, s30, 0x2000
	s_nop 0
	global_load_lds_dwordx4 v138, s[2:3]
	s_mov_b32 m0, s39
	s_nop 0
	global_load_lds_dwordx4 v132, s[100:101]
	s_mov_b32 m0, s40
	s_nop 0
	global_load_lds_dwordx4 v136, s[100:101]
	s_waitcnt vmcnt(8)
	s_waitcnt lgkmcnt(0)
	s_barrier
	s_setprio 1
	s_waitcnt lgkmcnt(0)
	v_mfma_f32_16x16x32_bf16 v[60:63], v[150:153], v[190:193], v[60:63]
	v_mfma_f32_16x16x32_bf16 v[56:59], v[166:169], v[190:193], v[56:59]
	v_mfma_f32_16x16x32_bf16 v[44:47], v[150:153], v[198:201], v[44:47]
	v_mfma_f32_16x16x32_bf16 v[40:43], v[166:169], v[198:201], v[40:43]
	v_mfma_f32_16x16x32_bf16 v[28:31], v[150:153], v[206:209], v[28:31]
	v_mfma_f32_16x16x32_bf16 v[24:27], v[166:169], v[206:209], v[24:27]
	v_mfma_f32_16x16x32_bf16 v[12:15], v[150:153], v[214:217], v[12:15]
	v_mfma_f32_16x16x32_bf16 v[8:11], v[166:169], v[214:217], v[8:11]
	v_mfma_f32_16x16x32_bf16 v[60:63], v[162:165], v[194:197], v[60:63]
	v_mfma_f32_16x16x32_bf16 v[56:59], v[170:173], v[194:197], v[56:59]
	v_mfma_f32_16x16x32_bf16 v[44:47], v[162:165], v[202:205], v[44:47]
	v_mfma_f32_16x16x32_bf16 v[40:43], v[170:173], v[202:205], v[40:43]
	v_mfma_f32_16x16x32_bf16 v[28:31], v[162:165], v[210:213], v[28:31]
	v_mfma_f32_16x16x32_bf16 v[24:27], v[170:173], v[210:213], v[24:27]
	v_mfma_f32_16x16x32_bf16 v[12:15], v[162:165], v[218:221], v[12:15]
	v_mfma_f32_16x16x32_bf16 v[8:11], v[170:173], v[218:221], v[8:11]
	s_setprio 0
	s_setprio 1
	v_mfma_f32_16x16x32_bf16 v[52:55], v[174:177], v[190:193], v[52:55]
	v_mfma_f32_16x16x32_bf16 v[48:51], v[182:185], v[190:193], v[48:51]
	v_mfma_f32_16x16x32_bf16 v[36:39], v[174:177], v[198:201], v[36:39]
	v_mfma_f32_16x16x32_bf16 v[32:35], v[182:185], v[198:201], v[32:35]
	v_mfma_f32_16x16x32_bf16 v[20:23], v[174:177], v[206:209], v[20:23]
	v_mfma_f32_16x16x32_bf16 v[16:19], v[182:185], v[206:209], v[16:19]
	v_mfma_f32_16x16x32_bf16 v[4:7], v[174:177], v[214:217], v[4:7]
	v_mfma_f32_16x16x32_bf16 v[0:3], v[182:185], v[214:217], v[0:3]
	v_mfma_f32_16x16x32_bf16 v[52:55], v[178:181], v[194:197], v[52:55]
	v_mfma_f32_16x16x32_bf16 v[48:51], v[186:189], v[194:197], v[48:51]
	v_mfma_f32_16x16x32_bf16 v[36:39], v[178:181], v[202:205], v[36:39]
	v_mfma_f32_16x16x32_bf16 v[32:35], v[186:189], v[202:205], v[32:35]
	v_mfma_f32_16x16x32_bf16 v[20:23], v[178:181], v[210:213], v[20:23]
	v_mfma_f32_16x16x32_bf16 v[16:19], v[186:189], v[210:213], v[16:19]
	v_mfma_f32_16x16x32_bf16 v[4:7], v[178:181], v[218:221], v[4:7]
	v_mfma_f32_16x16x32_bf16 v[0:3], v[186:189], v[218:221], v[0:3]
	s_setprio 0
	s_barrier
	s_add_i32 s50, s50, 2
	s_add_u32 s28, s28, 0x100
	s_addc_u32 s29, s29, 0
	s_add_u32 s48, s48, 0x100
	s_addc_u32 s49, s49, 0
	s_cmpk_gt_u32 s50, 0x7d
	s_cbranch_scc0 .LBB0_717
	s_and_b64 vcc, exec, s[16:17]
	s_cbranch_vccz .LBB0_720
	s_barrier
